# P0: non-temporal hint on the once-read f32 weight loads
# speedup vs baseline: 1.0022x; 1.0022x over previous
; #define LAS __attribute__((address_space(3)))
; __device__ __forceinline__ void transpose_item(const float* W, int K, int N, int NP, int kind, bf16_t* WT, LAS float* scr, int item, int lane) {
;     const int nblk = NP / 32, kb = item / nblk, nb = item % nblk, k0 = 64 * kb, n0 = 32 * nb;
;     bool rp; const int sb = src_group_base(kind, n0, rp);
;     const int p = lane & 31; const int so = rp ? (4 * (p >> 3) + (p & 3) + 16 * ((p >> 2) & 1)) : p;
; #pragma unroll 8
;     for (int i = 0; i < 32; ++i) { const int kk = 2 * i + (lane >> 5); scr[kk * 33 + p] = W[(size_t)(k0 + kk) * N + sb + so]; }
;     asm volatile("s_waitcnt lgkmcnt(0)" ::: "memory");
.LBB0_490:
	s_lshl_b32 s20, s12, 1
	s_lshl_b32 s19, s11, 1
	v_or_b32_e32 v176, s20, v10
	s_add_i32 s15, s20, 4
	s_add_i32 s14, s19, 4
	s_add_i32 s24, s19, 8
	s_add_i32 s25, s20, 8
	v_lshlrev_b64 v[32:33], 13, v[176:177]
	v_or_b32_e32 v176, s15, v10
	v_mov_b32_e32 v17, v177
	v_mov_b32_e32 v19, v177
	v_mov_b32_e32 v21, v177
	v_or_b32_e32 v16, s19, v3
	s_add_i32 s26, s19, 12
	s_add_i32 s27, s20, 12
	s_add_i32 s28, s19, 16
	s_add_i32 s30, s19, 20
	s_add_i32 s34, s19, 24
	s_add_i32 s37, s19, 28
	v_or_b32_e32 v18, s14, v3
	v_or_b32_e32 v20, s24, v3
	v_lshlrev_b64 v[34:35], 13, v[176:177]
	v_or_b32_e32 v176, s25, v10
	v_mov_b32_e32 v23, v177
	v_mov_b32_e32 v25, v177
	v_mov_b32_e32 v27, v177
	v_mov_b32_e32 v29, v177
	v_mov_b32_e32 v31, v177
	s_add_i32 s29, s20, 16
	v_lshlrev_b64 v[16:17], 13, v[16:17]
	v_or_b32_e32 v22, s26, v3
	v_or_b32_e32 v24, s28, v3
	v_or_b32_e32 v26, s30, v3
	v_or_b32_e32 v28, s34, v3
	v_or_b32_e32 v30, s37, v3
	v_lshl_add_u64 v[32:33], v[8:9], 0, v[32:33]
	v_lshlrev_b64 v[18:19], 13, v[18:19]
	v_lshlrev_b64 v[20:21], 13, v[20:21]
	v_lshlrev_b64 v[36:37], 13, v[176:177]
	v_or_b32_e32 v176, s27, v10
	s_add_i32 s31, s20, 20
	v_lshl_add_u64 v[16:17], v[8:9], 0, v[16:17]
	v_lshlrev_b64 v[22:23], 13, v[22:23]
	v_lshlrev_b64 v[24:25], 13, v[24:25]
	v_lshlrev_b64 v[26:27], 13, v[26:27]
	v_lshlrev_b64 v[28:29], 13, v[28:29]
	v_lshlrev_b64 v[30:31], 13, v[30:31]
	v_lshl_add_u64 v[34:35], v[8:9], 0, v[34:35]
	v_lshl_add_u64 v[18:19], v[8:9], 0, v[18:19]
	v_lshl_add_u64 v[20:21], v[8:9], 0, v[20:21]
	global_load_dword v48, v[32:33], off nt
	global_load_dword v49, v[16:17], off nt
	v_lshlrev_b64 v[32:33], 13, v[176:177]
	v_or_b32_e32 v176, s29, v10
	s_add_i32 s35, s20, 24
	v_lshl_add_u64 v[22:23], v[8:9], 0, v[22:23]
	v_lshl_add_u64 v[24:25], v[8:9], 0, v[24:25]
	v_lshl_add_u64 v[26:27], v[8:9], 0, v[26:27]
	v_lshl_add_u64 v[28:29], v[8:9], 0, v[28:29]
	v_lshl_add_u64 v[30:31], v[8:9], 0, v[30:31]
	global_load_dword v50, v[34:35], off nt
	global_load_dword v51, v[18:19], off nt
	global_load_dword v52, v[20:21], off nt
	global_load_dword v53, v[22:23], off nt
	global_load_dword v54, v[24:25], off nt
	global_load_dword v55, v[26:27], off nt
	global_load_dword v56, v[28:29], off nt
	global_load_dword v57, v[30:31], off nt
	v_lshl_add_u64 v[18:19], v[8:9], 0, v[32:33]
	v_lshlrev_b64 v[20:21], 13, v[176:177]
	v_or_b32_e32 v176, s31, v10
	s_add_i32 s38, s20, 28
	v_lshl_add_u64 v[16:17], v[8:9], 0, v[36:37]
	global_load_dword v58, v[18:19], off nt
	global_load_dword v59, v[16:17], off nt
	v_lshlrev_b64 v[18:19], 13, v[176:177]
	v_or_b32_e32 v176, s35, v10
	v_lshl_add_u64 v[16:17], v[8:9], 0, v[20:21]
	v_lshlrev_b64 v[20:21], 13, v[176:177]
	v_or_b32_e32 v176, s38, v10
	v_lshlrev_b64 v[22:23], 13, v[176:177]
	v_lshl_add_u64 v[22:23], v[8:9], 0, v[22:23]
	v_lshl_add_u64 v[18:19], v[8:9], 0, v[18:19]
	v_lshl_add_u64 v[20:21], v[8:9], 0, v[20:21]
	global_load_dword v60, v[22:23], off nt
	global_load_dword v61, v[20:21], off nt
	global_load_dword v62, v[18:19], off nt
	global_load_dword v63, v[16:17], off nt
	v_or_b32_e32 v18, s19, v1
	v_or_b32_e32 v16, s20, v2
	s_add_i32 s12, s12, 16
	s_add_i32 s11, s11, 16
	s_add_i32 s13, s13, -16
	v_mad_u64_u32 v[16:17], s[20:21], v16, s49, v[4:5]
	v_mad_u64_u32 v[18:19], s[20:21], v18, s49, v[4:5]
	v_or_b32_e32 v17, s14, v1
	v_or_b32_e32 v19, s15, v2
	v_or_b32_e32 v26, s24, v1
	v_or_b32_e32 v24, s25, v2
	v_or_b32_e32 v30, s26, v1
	v_or_b32_e32 v28, s27, v2
	v_or_b32_e32 v34, s28, v1
	v_or_b32_e32 v32, s29, v2
	v_or_b32_e32 v38, s30, v1
	v_or_b32_e32 v36, s31, v2
	v_or_b32_e32 v42, s34, v1
	v_or_b32_e32 v40, s35, v2
	v_or_b32_e32 v46, s37, v1
	v_or_b32_e32 v44, s38, v2
	s_cmp_lg_u32 s13, 0
	v_mad_u64_u32 v[20:21], s[20:21], v19, s49, v[4:5]
	v_mad_u64_u32 v[22:23], s[20:21], v17, s49, v[4:5]
	v_mad_u64_u32 v[24:25], s[20:21], v24, s49, v[4:5]
	v_mad_u64_u32 v[26:27], s[20:21], v26, s49, v[4:5]
	v_mad_u64_u32 v[28:29], s[20:21], v28, s49, v[4:5]
	v_mad_u64_u32 v[30:31], s[20:21], v30, s49, v[4:5]
	v_mad_u64_u32 v[32:33], s[20:21], v32, s49, v[4:5]
	v_mad_u64_u32 v[34:35], s[20:21], v34, s49, v[4:5]
	v_mad_u64_u32 v[36:37], s[20:21], v36, s49, v[4:5]
	v_mad_u64_u32 v[38:39], s[20:21], v38, s49, v[4:5]
	v_mad_u64_u32 v[40:41], s[20:21], v40, s49, v[4:5]
	v_mad_u64_u32 v[42:43], s[20:21], v42, s49, v[4:5]
	v_mad_u64_u32 v[44:45], s[20:21], v44, s49, v[4:5]
	v_mad_u64_u32 v[46:47], s[20:21], v46, s49, v[4:5]
	s_waitcnt vmcnt(0)
	ds_write_b32 v16, v48
	ds_write_b32 v18, v49
	ds_write_b32 v20, v50
	ds_write_b32 v22, v51
	ds_write_b32 v24, v59
	ds_write_b32 v26, v52
	ds_write_b32 v28, v58
	ds_write_b32 v30, v53
	ds_write_b32 v32, v63
	ds_write_b32 v34, v54
	ds_write_b32 v36, v62
	ds_write_b32 v38, v55
	ds_write_b32 v40, v61
	ds_write_b32 v42, v56
	ds_write_b32 v44, v60
	ds_write_b32 v46, v57
	s_cbranch_scc1 .LBB0_490
; #define LAS __attribute__((address_space(3)))
; __device__ __forceinline__ unsigned cvt_pk_bf16(float lo, float hi) { unsigned r; asm volatile("v_cvt_pk_bf16_f32 %0, %1, %2" : "=v"(r) : "v"(lo), "v"(hi)); return r; }
; __device__ __forceinline__ void transpose_item(const float* W, int K, int N, int NP, int kind, bf16_t* WT, LAS float* scr, int item, int lane) {
;     ...
;     const int c = lane & 7;
; #pragma unroll
;     for (int j = 0; j < 4; ++j) { const int n = (lane >> 3) + 8 * j; const LAS float* s = scr + (8 * c) * 33 + n;
;         u32x4 o; o.x = cvt_pk_bf16(s[0 * 33], s[1 * 33]); o.y = cvt_pk_bf16(s[2 * 33], s[3 * 33]); o.z = cvt_pk_bf16(s[4 * 33], s[5 * 33]); o.w = cvt_pk_bf16(s[6 * 33], s[7 * 33]);
;         *(u32x4*)(WT + (size_t)(n0 + n) * K + k0 + 8 * c) = o; }
;     asm volatile("s_waitcnt lgkmcnt(0)" ::: "memory");
	s_waitcnt lgkmcnt(0)
	s_lshl_b32 s9, s9, 1
	ds_read2_b32 v[8:9], v11 offset1:33
	s_add_u32 s12, s18, s9
	s_waitcnt lgkmcnt(0)
	v_cvt_pk_bf16_f32 v16, v8, v9
	ds_read2_b32 v[8:9], v11 offset0:66 offset1:99
	v_lshlrev_b32_e32 v176, 1, v6
	v_or_b32_e32 v3, s8, v7
	s_addc_u32 s13, s4, 0
	s_waitcnt lgkmcnt(0)
	v_cvt_pk_bf16_f32 v17, v8, v9
	ds_read2_b32 v[8:9], v11 offset0:132 offset1:165
	v_mul_u32_u24_e32 v3, 0x1600, v3
	v_lshl_add_u64 v[20:21], s[12:13], 0, v[176:177]
	s_mov_b64 s[12:13], 0x7600000
	s_waitcnt lgkmcnt(0)
	v_cvt_pk_bf16_f32 v18, v8, v9
	ds_read2_b32 v[8:9], v11 offset0:198 offset1:231
	v_lshlrev_b32_e32 v176, 1, v3
	v_lshl_add_u64 v[20:21], v[20:21], 0, s[12:13]
	s_waitcnt lgkmcnt(0)
	v_cvt_pk_bf16_f32 v19, v8, v9
	ds_read2_b32 v[8:9], v11 offset0:8 offset1:41
	v_lshl_add_u64 v[22:23], v[20:21], 0, v[176:177]
	global_store_dwordx4 v[22:23], v[16:19], off
	v_or_b32_e32 v3, s8, v12
	v_mul_u32_u24_e32 v3, 0x1600, v3
	s_waitcnt lgkmcnt(0)
	v_cvt_pk_bf16_f32 v16, v8, v9
	ds_read2_b32 v[8:9], v11 offset0:74 offset1:107
	s_waitcnt lgkmcnt(0)
	v_cvt_pk_bf16_f32 v17, v8, v9
	ds_read2_b32 v[8:9], v11 offset0:140 offset1:173
	s_waitcnt lgkmcnt(0)
	v_cvt_pk_bf16_f32 v18, v8, v9
	ds_read2_b32 v[8:9], v11 offset0:206 offset1:239
	v_lshlrev_b32_e32 v176, 1, v3
	s_waitcnt lgkmcnt(0)
	v_cvt_pk_bf16_f32 v19, v8, v9
	ds_read2_b32 v[8:9], v11 offset0:16 offset1:49
	v_lshl_add_u64 v[22:23], v[20:21], 0, v[176:177]
	global_store_dwordx4 v[22:23], v[16:19], off
	v_or_b32_e32 v3, s8, v13
	v_mul_u32_u24_e32 v3, 0x1600, v3
	s_waitcnt lgkmcnt(0)
	v_cvt_pk_bf16_f32 v16, v8, v9
	ds_read2_b32 v[8:9], v11 offset0:82 offset1:115
	s_waitcnt lgkmcnt(0)
	v_cvt_pk_bf16_f32 v17, v8, v9
	ds_read2_b32 v[8:9], v11 offset0:148 offset1:181
	s_waitcnt lgkmcnt(0)
	v_cvt_pk_bf16_f32 v18, v8, v9
	ds_read2_b32 v[8:9], v11 offset0:214 offset1:247
	v_lshlrev_b32_e32 v176, 1, v3
	s_waitcnt lgkmcnt(0)
	v_cvt_pk_bf16_f32 v19, v8, v9
	ds_read2_b32 v[8:9], v11 offset0:24 offset1:57
	v_lshl_add_u64 v[22:23], v[20:21], 0, v[176:177]
	global_store_dwordx4 v[22:23], v[16:19], off
	v_or_b32_e32 v3, s8, v14
	v_mul_u32_u24_e32 v3, 0x1600, v3
	s_waitcnt lgkmcnt(0)
	v_cvt_pk_bf16_f32 v16, v8, v9
	ds_read2_b32 v[8:9], v11 offset0:90 offset1:123
	s_waitcnt lgkmcnt(0)
	v_cvt_pk_bf16_f32 v17, v8, v9
	ds_read2_b32 v[8:9], v11 offset0:156 offset1:189
	s_waitcnt lgkmcnt(0)
	v_cvt_pk_bf16_f32 v18, v8, v9
	ds_read2_b32 v[8:9], v11 offset0:222 offset1:255
	v_lshlrev_b32_e32 v176, 1, v3
	s_waitcnt lgkmcnt(0)
	v_cvt_pk_bf16_f32 v19, v8, v9
	v_lshl_add_u64 v[8:9], v[20:21], 0, v[176:177]
	global_store_dwordx4 v[8:9], v[16:19], off
	s_waitcnt lgkmcnt(0)
	s_mov_b64 s[8:9], 0
	s_mov_b64 s[38:39], 0x800

; #define LAS __attribute__((address_space(3)))
; __device__ __forceinline__ unsigned cvt_pk_bf16(float lo, float hi) { unsigned r; asm volatile("v_cvt_pk_bf16_f32 %0, %1, %2" : "=v"(r) : "v"(lo), "v"(hi)); return r; }
; __device__ __forceinline__ void transpose_item(const float* W, int K, int N, int NP, int kind, bf16_t* WT, LAS float* scr, int item, int lane) {
;     const int nblk = NP / 32, kb = item / nblk, nb = item % nblk, k0 = 64 * kb, n0 = 32 * nb;
;     bool rp; const int sb = src_group_base(kind, n0, rp);
;     const int p = lane & 31; const int so = rp ? (4 * (p >> 3) + (p & 3) + 16 * ((p >> 2) & 1)) : p;
; #pragma unroll 8
;     for (int i = 0; i < 32; ++i) { const int kk = 2 * i + (lane >> 5); scr[kk * 33 + p] = W[(size_t)(k0 + kk) * N + sb + so]; }
;     asm volatile("s_waitcnt lgkmcnt(0)" ::: "memory");
;     const int c = lane & 7;
; #pragma unroll
;     for (int j = 0; j < 4; ++j) { const int n = (lane >> 3) + 8 * j; const LAS float* s = scr + (8 * c) * 33 + n;
;         u32x4 o; o.x = cvt_pk_bf16(s[0 * 33], s[1 * 33]); o.y = cvt_pk_bf16(s[2 * 33], s[3 * 33]); o.z = cvt_pk_bf16(s[4 * 33], s[5 * 33]); o.w = cvt_pk_bf16(s[6 * 33], s[7 * 33]);
;         *(u32x4*)(WT + (size_t)(n0 + n) * K + k0 + 8 * c) = o; }
;     asm volatile("s_waitcnt lgkmcnt(0)" ::: "memory");
.LBB0_494:
	s_lshl_b32 s14, s11, 1
	s_lshl_b32 s15, s12, 1
	v_or_b32_e32 v16, s15, v10
	s_add_i32 s19, s14, 4
	s_add_i32 s24, s15, 4
	s_add_i32 s25, s14, 8
	s_add_i32 s26, s15, 8
	s_add_i32 s27, s14, 12
	s_add_i32 s28, s15, 12
	s_add_i32 s29, s14, 16
	s_add_i32 s30, s15, 16
	s_add_i32 s31, s14, 20
	s_add_i32 s34, s15, 20
	s_add_i32 s35, s14, 24
	s_add_i32 s37, s15, 24
	s_add_i32 s38, s14, 28
	s_add_i32 s39, s15, 28
	v_or_b32_e32 v18, s14, v3
	v_mad_u64_u32 v[16:17], s[20:21], v16, s61, v[8:9]
	v_or_b32_e32 v22, s19, v3
	v_or_b32_e32 v20, s24, v10
	v_or_b32_e32 v26, s25, v3
	v_or_b32_e32 v24, s26, v10
	v_or_b32_e32 v30, s27, v3
	v_or_b32_e32 v28, s28, v10
	v_or_b32_e32 v34, s29, v3
	v_or_b32_e32 v32, s30, v10
	v_or_b32_e32 v38, s31, v3
	v_or_b32_e32 v36, s34, v10
	v_or_b32_e32 v42, s35, v3
	v_or_b32_e32 v40, s37, v10
	v_or_b32_e32 v46, s38, v3
	v_or_b32_e32 v44, s39, v10
	v_mad_u64_u32 v[18:19], s[20:21], v18, s61, v[8:9]
	v_mad_u64_u32 v[20:21], s[20:21], v20, s61, v[8:9]
	v_mad_u64_u32 v[22:23], s[20:21], v22, s61, v[8:9]
	v_mad_u64_u32 v[24:25], s[20:21], v24, s61, v[8:9]
	v_mad_u64_u32 v[26:27], s[20:21], v26, s61, v[8:9]
	v_mad_u64_u32 v[28:29], s[20:21], v28, s61, v[8:9]
	v_mad_u64_u32 v[30:31], s[20:21], v30, s61, v[8:9]
	v_mad_u64_u32 v[32:33], s[20:21], v32, s61, v[8:9]
	v_mad_u64_u32 v[34:35], s[20:21], v34, s61, v[8:9]
	v_mad_u64_u32 v[36:37], s[20:21], v36, s61, v[8:9]
	v_mad_u64_u32 v[38:39], s[20:21], v38, s61, v[8:9]
	v_mad_u64_u32 v[40:41], s[20:21], v40, s61, v[8:9]
	v_mad_u64_u32 v[42:43], s[20:21], v42, s61, v[8:9]
	v_mad_u64_u32 v[44:45], s[20:21], v44, s61, v[8:9]
	v_mad_u64_u32 v[46:47], s[20:21], v46, s61, v[8:9]
	global_load_dword v48, v[16:17], off nt
	global_load_dword v49, v[18:19], off nt
	global_load_dword v50, v[20:21], off nt
	global_load_dword v51, v[22:23], off nt
	global_load_dword v52, v[24:25], off nt
	global_load_dword v53, v[26:27], off nt
	global_load_dword v54, v[28:29], off nt
	global_load_dword v55, v[30:31], off nt
	global_load_dword v56, v[32:33], off nt
	global_load_dword v57, v[34:35], off nt
	global_load_dword v58, v[36:37], off nt
	global_load_dword v59, v[38:39], off nt
	global_load_dword v60, v[40:41], off nt
	global_load_dword v61, v[42:43], off nt
	global_load_dword v62, v[44:45], off nt
	global_load_dword v63, v[46:47], off nt
	v_or_b32_e32 v18, s14, v1
	v_or_b32_e32 v16, s15, v2
	s_add_i32 s12, s12, 16
	s_add_i32 s11, s11, 16
	s_add_i32 s13, s13, -16
	v_mad_u64_u32 v[16:17], s[20:21], v16, s49, v[4:5]
	v_mad_u64_u32 v[18:19], s[20:21], v18, s49, v[4:5]
	v_or_b32_e32 v17, s19, v1
	v_or_b32_e32 v19, s24, v2
	v_or_b32_e32 v26, s25, v1
	v_or_b32_e32 v24, s26, v2
	v_or_b32_e32 v30, s27, v1
	v_or_b32_e32 v28, s28, v2
	v_or_b32_e32 v34, s29, v1
	v_or_b32_e32 v32, s30, v2
	v_or_b32_e32 v38, s31, v1
	v_or_b32_e32 v36, s34, v2
	v_or_b32_e32 v42, s35, v1
	v_or_b32_e32 v40, s37, v2
	v_or_b32_e32 v46, s38, v1
	v_or_b32_e32 v44, s39, v2
	s_cmp_lg_u32 s13, 0
	v_mad_u64_u32 v[20:21], s[20:21], v19, s49, v[4:5]
	v_mad_u64_u32 v[22:23], s[20:21], v17, s49, v[4:5]
	v_mad_u64_u32 v[24:25], s[20:21], v24, s49, v[4:5]
	v_mad_u64_u32 v[26:27], s[20:21], v26, s49, v[4:5]
	v_mad_u64_u32 v[28:29], s[20:21], v28, s49, v[4:5]
	v_mad_u64_u32 v[30:31], s[20:21], v30, s49, v[4:5]
	v_mad_u64_u32 v[32:33], s[20:21], v32, s49, v[4:5]
	v_mad_u64_u32 v[34:35], s[20:21], v34, s49, v[4:5]
	v_mad_u64_u32 v[36:37], s[20:21], v36, s49, v[4:5]
	v_mad_u64_u32 v[38:39], s[20:21], v38, s49, v[4:5]
	v_mad_u64_u32 v[40:41], s[20:21], v40, s49, v[4:5]
	v_mad_u64_u32 v[42:43], s[20:21], v42, s49, v[4:5]
	v_mad_u64_u32 v[44:45], s[20:21], v44, s49, v[4:5]
	v_mad_u64_u32 v[46:47], s[20:21], v46, s49, v[4:5]
	s_waitcnt vmcnt(0)
	ds_write_b32 v16, v48
	ds_write_b32 v18, v49
	ds_write_b32 v20, v50
	ds_write_b32 v22, v51
	ds_write_b32 v24, v52
	ds_write_b32 v26, v53
	ds_write_b32 v28, v54
	ds_write_b32 v30, v55
	ds_write_b32 v32, v56
	ds_write_b32 v34, v57
	ds_write_b32 v36, v58
	ds_write_b32 v38, v59
	ds_write_b32 v40, v60
	ds_write_b32 v42, v61
	ds_write_b32 v44, v62
	ds_write_b32 v46, v63
	s_cbranch_scc1 .LBB0_494
	s_and_b32 s9, 0xffff, s9
	s_waitcnt lgkmcnt(0)
	s_lshl_b32 s9, s9, 1
	ds_read2_b32 v[8:9], v11 offset1:33
	s_add_u32 s12, s18, s9
	s_waitcnt lgkmcnt(0)
	v_cvt_pk_bf16_f32 v16, v8, v9
	ds_read2_b32 v[8:9], v11 offset0:66 offset1:99
	v_lshlrev_b32_e32 v176, 1, v6
	s_addc_u32 s13, s4, 0
	s_waitcnt lgkmcnt(0)
	v_cvt_pk_bf16_f32 v17, v8, v9
	ds_read2_b32 v[8:9], v11 offset0:132 offset1:165
	v_or_b32_e32 v3, s8, v7
	v_lshl_add_u64 v[20:21], s[12:13], 0, v[176:177]
	s_mov_b64 s[12:13], 0x4a00000
	s_waitcnt lgkmcnt(0)
	v_cvt_pk_bf16_f32 v18, v8, v9
	ds_read2_b32 v[8:9], v11 offset0:198 offset1:231
	v_lshlrev_b32_e32 v176, 12, v3
	v_lshl_add_u64 v[20:21], v[20:21], 0, s[12:13]
	s_waitcnt lgkmcnt(0)
	v_cvt_pk_bf16_f32 v19, v8, v9
	ds_read2_b32 v[8:9], v11 offset0:8 offset1:41
	v_lshl_add_u64 v[22:23], v[20:21], 0, v[176:177]
	global_store_dwordx4 v[22:23], v[16:19], off
	v_or_b32_e32 v3, s8, v12
	v_lshlrev_b32_e32 v176, 12, v3
	s_waitcnt lgkmcnt(0)
	v_cvt_pk_bf16_f32 v16, v8, v9
	ds_read2_b32 v[8:9], v11 offset0:74 offset1:107
	s_waitcnt lgkmcnt(0)
	v_cvt_pk_bf16_f32 v17, v8, v9
	ds_read2_b32 v[8:9], v11 offset0:140 offset1:173
	s_waitcnt lgkmcnt(0)
	v_cvt_pk_bf16_f32 v18, v8, v9
	ds_read2_b32 v[8:9], v11 offset0:206 offset1:239
	s_waitcnt lgkmcnt(0)
	v_cvt_pk_bf16_f32 v19, v8, v9
	ds_read2_b32 v[8:9], v11 offset0:16 offset1:49
	v_lshl_add_u64 v[22:23], v[20:21], 0, v[176:177]
	global_store_dwordx4 v[22:23], v[16:19], off
	v_or_b32_e32 v3, s8, v13
	v_lshlrev_b32_e32 v176, 12, v3
	s_waitcnt lgkmcnt(0)
	v_cvt_pk_bf16_f32 v16, v8, v9
	ds_read2_b32 v[8:9], v11 offset0:82 offset1:115
	s_waitcnt lgkmcnt(0)
	v_cvt_pk_bf16_f32 v17, v8, v9
	ds_read2_b32 v[8:9], v11 offset0:148 offset1:181
	s_waitcnt lgkmcnt(0)
	v_cvt_pk_bf16_f32 v18, v8, v9
	ds_read2_b32 v[8:9], v11 offset0:214 offset1:247
	s_waitcnt lgkmcnt(0)
	v_cvt_pk_bf16_f32 v19, v8, v9
	ds_read2_b32 v[8:9], v11 offset0:24 offset1:57
	v_lshl_add_u64 v[22:23], v[20:21], 0, v[176:177]
	global_store_dwordx4 v[22:23], v[16:19], off
	v_or_b32_e32 v3, s8, v14
	v_lshlrev_b32_e32 v176, 12, v3
	s_waitcnt lgkmcnt(0)
	v_cvt_pk_bf16_f32 v16, v8, v9
	ds_read2_b32 v[8:9], v11 offset0:90 offset1:123
	s_waitcnt lgkmcnt(0)
	v_cvt_pk_bf16_f32 v17, v8, v9
	ds_read2_b32 v[8:9], v11 offset0:156 offset1:189
	s_waitcnt lgkmcnt(0)
	v_cvt_pk_bf16_f32 v18, v8, v9
	ds_read2_b32 v[8:9], v11 offset0:222 offset1:255
	s_waitcnt lgkmcnt(0)
	v_cvt_pk_bf16_f32 v19, v8, v9
	v_lshl_add_u64 v[8:9], v[20:21], 0, v[176:177]
	global_store_dwordx4 v[8:9], v[16:19], off
	s_waitcnt lgkmcnt(0)
	s_mov_b64 s[38:39], 0x800
	s_mov_b32 s64, s16

; #define LAS __attribute__((address_space(3)))
; __device__ __forceinline__ void transpose_item(const float* W, int K, int N, int NP, int kind, bf16_t* WT, LAS float* scr, int item, int lane) {
;     const int nblk = NP / 32, kb = item / nblk, nb = item % nblk, k0 = 64 * kb, n0 = 32 * nb;
;     bool rp; const int sb = src_group_base(kind, n0, rp);
;     const int p = lane & 31; const int so = rp ? (4 * (p >> 3) + (p & 3) + 16 * ((p >> 2) & 1)) : p;
; #pragma unroll 8
;     for (int i = 0; i < 32; ++i) { const int kk = 2 * i + (lane >> 5); scr[kk * 33 + p] = W[(size_t)(k0 + kk) * N + sb + so]; }
.LBB0_499:
	s_lshl_b32 s20, s12, 1
	s_lshl_b32 s19, s11, 1
	v_or_b32_e32 v176, s20, v10
	s_add_i32 s15, s20, 4
	s_add_i32 s14, s19, 4
	s_add_i32 s24, s19, 8
	s_add_i32 s25, s20, 8
	v_lshlrev_b64 v[32:33], 13, v[176:177]
	v_or_b32_e32 v176, s15, v10
	v_mov_b32_e32 v17, v177
	v_mov_b32_e32 v19, v177
	v_mov_b32_e32 v21, v177
	v_or_b32_e32 v16, s19, v3
	s_add_i32 s26, s19, 12
	s_add_i32 s27, s20, 12
	s_add_i32 s28, s19, 16
	s_add_i32 s30, s19, 20
	s_add_i32 s34, s19, 24
	s_add_i32 s37, s19, 28
	v_or_b32_e32 v18, s14, v3
	v_or_b32_e32 v20, s24, v3
	v_lshlrev_b64 v[34:35], 13, v[176:177]
	v_or_b32_e32 v176, s25, v10
	v_mov_b32_e32 v23, v177
	v_mov_b32_e32 v25, v177
	v_mov_b32_e32 v27, v177
	v_mov_b32_e32 v29, v177
	v_mov_b32_e32 v31, v177
	s_add_i32 s29, s20, 16
	v_lshlrev_b64 v[16:17], 13, v[16:17]
	v_or_b32_e32 v22, s26, v3
	v_or_b32_e32 v24, s28, v3
	v_or_b32_e32 v26, s30, v3
	v_or_b32_e32 v28, s34, v3
	v_or_b32_e32 v30, s37, v3
	v_lshl_add_u64 v[32:33], v[8:9], 0, v[32:33]
	v_lshlrev_b64 v[18:19], 13, v[18:19]
	v_lshlrev_b64 v[20:21], 13, v[20:21]
	v_lshlrev_b64 v[36:37], 13, v[176:177]
	v_or_b32_e32 v176, s27, v10
	s_add_i32 s31, s20, 20
	v_lshl_add_u64 v[16:17], v[8:9], 0, v[16:17]
	v_lshlrev_b64 v[22:23], 13, v[22:23]
	v_lshlrev_b64 v[24:25], 13, v[24:25]
	v_lshlrev_b64 v[26:27], 13, v[26:27]
	v_lshlrev_b64 v[28:29], 13, v[28:29]
	v_lshlrev_b64 v[30:31], 13, v[30:31]
	v_lshl_add_u64 v[34:35], v[8:9], 0, v[34:35]
	v_lshl_add_u64 v[18:19], v[8:9], 0, v[18:19]
	v_lshl_add_u64 v[20:21], v[8:9], 0, v[20:21]
	global_load_dword v48, v[32:33], off nt
	global_load_dword v49, v[16:17], off nt
	v_lshlrev_b64 v[32:33], 13, v[176:177]
	v_or_b32_e32 v176, s29, v10
	s_add_i32 s35, s20, 24
	v_lshl_add_u64 v[22:23], v[8:9], 0, v[22:23]
	v_lshl_add_u64 v[24:25], v[8:9], 0, v[24:25]
	v_lshl_add_u64 v[26:27], v[8:9], 0, v[26:27]
	v_lshl_add_u64 v[28:29], v[8:9], 0, v[28:29]
	v_lshl_add_u64 v[30:31], v[8:9], 0, v[30:31]
	global_load_dword v50, v[34:35], off nt
	global_load_dword v51, v[18:19], off nt
	global_load_dword v52, v[20:21], off nt
	global_load_dword v53, v[22:23], off nt
	global_load_dword v54, v[24:25], off nt
	global_load_dword v55, v[26:27], off nt
	global_load_dword v56, v[28:29], off nt
	global_load_dword v57, v[30:31], off nt
	v_lshl_add_u64 v[18:19], v[8:9], 0, v[32:33]
	v_lshlrev_b64 v[20:21], 13, v[176:177]
	v_or_b32_e32 v176, s31, v10
	s_add_i32 s38, s20, 28
	v_lshl_add_u64 v[16:17], v[8:9], 0, v[36:37]
	global_load_dword v58, v[18:19], off nt
	global_load_dword v59, v[16:17], off nt
	v_lshlrev_b64 v[18:19], 13, v[176:177]
	v_or_b32_e32 v176, s35, v10
	v_lshl_add_u64 v[16:17], v[8:9], 0, v[20:21]
	v_lshlrev_b64 v[20:21], 13, v[176:177]
	v_or_b32_e32 v176, s38, v10
	v_lshlrev_b64 v[22:23], 13, v[176:177]
	v_lshl_add_u64 v[22:23], v[8:9], 0, v[22:23]
	v_lshl_add_u64 v[18:19], v[8:9], 0, v[18:19]
	v_lshl_add_u64 v[20:21], v[8:9], 0, v[20:21]
	global_load_dword v60, v[22:23], off nt
	global_load_dword v61, v[20:21], off nt
	global_load_dword v62, v[18:19], off nt
	global_load_dword v63, v[16:17], off nt
	v_or_b32_e32 v18, s19, v1
	v_or_b32_e32 v16, s20, v2
	s_add_i32 s12, s12, 16
	s_add_i32 s11, s11, 16
	s_add_i32 s13, s13, -16
	v_mad_u64_u32 v[16:17], s[20:21], v16, s49, v[4:5]
	v_mad_u64_u32 v[18:19], s[20:21], v18, s49, v[4:5]
	v_or_b32_e32 v17, s14, v1
	v_or_b32_e32 v19, s15, v2
	v_or_b32_e32 v26, s24, v1
	v_or_b32_e32 v24, s25, v2
	v_or_b32_e32 v30, s26, v1
	v_or_b32_e32 v28, s27, v2
	v_or_b32_e32 v34, s28, v1
	v_or_b32_e32 v32, s29, v2
	v_or_b32_e32 v38, s30, v1
	v_or_b32_e32 v36, s31, v2
	v_or_b32_e32 v42, s34, v1
	v_or_b32_e32 v40, s35, v2
	v_or_b32_e32 v46, s37, v1
	v_or_b32_e32 v44, s38, v2
	s_cmp_lg_u32 s13, 0
	v_mad_u64_u32 v[20:21], s[20:21], v19, s49, v[4:5]
	v_mad_u64_u32 v[22:23], s[20:21], v17, s49, v[4:5]
	v_mad_u64_u32 v[24:25], s[20:21], v24, s49, v[4:5]
	v_mad_u64_u32 v[26:27], s[20:21], v26, s49, v[4:5]
	v_mad_u64_u32 v[28:29], s[20:21], v28, s49, v[4:5]
	v_mad_u64_u32 v[30:31], s[20:21], v30, s49, v[4:5]
	v_mad_u64_u32 v[32:33], s[20:21], v32, s49, v[4:5]
	v_mad_u64_u32 v[34:35], s[20:21], v34, s49, v[4:5]
	v_mad_u64_u32 v[36:37], s[20:21], v36, s49, v[4:5]
	v_mad_u64_u32 v[38:39], s[20:21], v38, s49, v[4:5]
	v_mad_u64_u32 v[40:41], s[20:21], v40, s49, v[4:5]
	v_mad_u64_u32 v[42:43], s[20:21], v42, s49, v[4:5]
	v_mad_u64_u32 v[44:45], s[20:21], v44, s49, v[4:5]
	v_mad_u64_u32 v[46:47], s[20:21], v46, s49, v[4:5]
	s_waitcnt vmcnt(0)
	ds_write_b32 v16, v48
	ds_write_b32 v18, v49
	ds_write_b32 v20, v50
	ds_write_b32 v22, v51
	ds_write_b32 v24, v59
	ds_write_b32 v26, v52
	ds_write_b32 v28, v58
	ds_write_b32 v30, v53
	ds_write_b32 v32, v63
	ds_write_b32 v34, v54
	ds_write_b32 v36, v62
	ds_write_b32 v38, v55
	ds_write_b32 v40, v61
	ds_write_b32 v42, v56
	ds_write_b32 v44, v60
	ds_write_b32 v46, v57
	s_cbranch_scc1 .LBB0_499
; #define LAS __attribute__((address_space(3)))
; __device__ __forceinline__ unsigned cvt_pk_bf16(float lo, float hi) { unsigned r; asm volatile("v_cvt_pk_bf16_f32 %0, %1, %2" : "=v"(r) : "v"(lo), "v"(hi)); return r; }
; __device__ __forceinline__ void transpose_item(const float* W, int K, int N, int NP, int kind, bf16_t* WT, LAS float* scr, int item, int lane) {
;     ...
;     asm volatile("s_waitcnt lgkmcnt(0)" ::: "memory");
;     const int c = lane & 7;
; #pragma unroll
;     for (int j = 0; j < 4; ++j) { const int n = (lane >> 3) + 8 * j; const LAS float* s = scr + (8 * c) * 33 + n;
;         u32x4 o; o.x = cvt_pk_bf16(s[0 * 33], s[1 * 33]); o.y = cvt_pk_bf16(s[2 * 33], s[3 * 33]); o.z = cvt_pk_bf16(s[4 * 33], s[5 * 33]); o.w = cvt_pk_bf16(s[6 * 33], s[7 * 33]);
;         *(u32x4*)(WT + (size_t)(n0 + n) * K + k0 + 8 * c) = o; }
;     asm volatile("s_waitcnt lgkmcnt(0)" ::: "memory");
	s_waitcnt lgkmcnt(0)
	s_lshl_b32 s9, s9, 1
	ds_read2_b32 v[8:9], v11 offset1:33
	s_add_u32 s12, s18, s9
	s_waitcnt lgkmcnt(0)
	v_cvt_pk_bf16_f32 v16, v8, v9
	ds_read2_b32 v[8:9], v11 offset0:66 offset1:99
	v_lshlrev_b32_e32 v176, 1, v6
	s_addc_u32 s13, s4, 0
	s_waitcnt lgkmcnt(0)
	v_cvt_pk_bf16_f32 v17, v8, v9
	ds_read2_b32 v[8:9], v11 offset0:132 offset1:165
	v_or_b32_e32 v3, s8, v7
	v_lshl_add_u64 v[20:21], s[12:13], 0, v[176:177]
	s_mov_b64 s[12:13], 0x4200000
	s_waitcnt lgkmcnt(0)
	v_cvt_pk_bf16_f32 v18, v8, v9
	ds_read2_b32 v[8:9], v11 offset0:198 offset1:231
	v_lshlrev_b32_e32 v176, 12, v3
	v_lshl_add_u64 v[20:21], v[20:21], 0, s[12:13]
	s_waitcnt lgkmcnt(0)
	v_cvt_pk_bf16_f32 v19, v8, v9
	ds_read2_b32 v[8:9], v11 offset0:8 offset1:41
	v_lshl_add_u64 v[22:23], v[20:21], 0, v[176:177]
	global_store_dwordx4 v[22:23], v[16:19], off
	v_or_b32_e32 v3, s8, v12
	v_lshlrev_b32_e32 v176, 12, v3
	s_waitcnt lgkmcnt(0)
	v_cvt_pk_bf16_f32 v16, v8, v9
	ds_read2_b32 v[8:9], v11 offset0:74 offset1:107
	s_waitcnt lgkmcnt(0)
	v_cvt_pk_bf16_f32 v17, v8, v9
	ds_read2_b32 v[8:9], v11 offset0:140 offset1:173
	s_waitcnt lgkmcnt(0)
	v_cvt_pk_bf16_f32 v18, v8, v9
	ds_read2_b32 v[8:9], v11 offset0:206 offset1:239
	s_waitcnt lgkmcnt(0)
	v_cvt_pk_bf16_f32 v19, v8, v9
	ds_read2_b32 v[8:9], v11 offset0:16 offset1:49
	v_lshl_add_u64 v[22:23], v[20:21], 0, v[176:177]
	global_store_dwordx4 v[22:23], v[16:19], off
	v_or_b32_e32 v3, s8, v13
	v_lshlrev_b32_e32 v176, 12, v3
	s_waitcnt lgkmcnt(0)
	v_cvt_pk_bf16_f32 v16, v8, v9
	ds_read2_b32 v[8:9], v11 offset0:82 offset1:115
	s_waitcnt lgkmcnt(0)
	v_cvt_pk_bf16_f32 v17, v8, v9
	ds_read2_b32 v[8:9], v11 offset0:148 offset1:181
	s_waitcnt lgkmcnt(0)
	v_cvt_pk_bf16_f32 v18, v8, v9
	ds_read2_b32 v[8:9], v11 offset0:214 offset1:247
	s_waitcnt lgkmcnt(0)
	v_cvt_pk_bf16_f32 v19, v8, v9
	ds_read2_b32 v[8:9], v11 offset0:24 offset1:57
	v_lshl_add_u64 v[22:23], v[20:21], 0, v[176:177]
	global_store_dwordx4 v[22:23], v[16:19], off
	v_or_b32_e32 v3, s8, v14
	v_lshlrev_b32_e32 v176, 12, v3
	s_waitcnt lgkmcnt(0)
	v_cvt_pk_bf16_f32 v16, v8, v9
	ds_read2_b32 v[8:9], v11 offset0:90 offset1:123
	s_waitcnt lgkmcnt(0)
	v_cvt_pk_bf16_f32 v17, v8, v9
	ds_read2_b32 v[8:9], v11 offset0:156 offset1:189
	s_waitcnt lgkmcnt(0)
	v_cvt_pk_bf16_f32 v18, v8, v9
	ds_read2_b32 v[8:9], v11 offset0:222 offset1:255
	s_waitcnt lgkmcnt(0)
	v_cvt_pk_bf16_f32 v19, v8, v9
	v_lshl_add_u64 v[8:9], v[20:21], 0, v[176:177]
	global_store_dwordx4 v[8:9], v[16:19], off
	s_waitcnt lgkmcnt(0)
	s_mov_b64 s[38:39], 0x800
	s_mov_b32 s64, s16

; #define LAS __attribute__((address_space(3)))
; __device__ __forceinline__ void transpose_item(const float* W, int K, int N, int NP, int kind, bf16_t* WT, LAS float* scr, int item, int lane) {
;     const int nblk = NP / 32, kb = item / nblk, nb = item % nblk, k0 = 64 * kb, n0 = 32 * nb;
;     bool rp; const int sb = src_group_base(kind, n0, rp);
;     const int p = lane & 31; const int so = rp ? (4 * (p >> 3) + (p & 3) + 16 * ((p >> 2) & 1)) : p;
; #pragma unroll 8
;     for (int i = 0; i < 32; ++i) { const int kk = 2 * i + (lane >> 5); scr[kk * 33 + p] = W[(size_t)(k0 + kk) * N + sb + so]; }
.LBB0_504:
	s_lshl_b32 s20, s12, 1
	s_lshl_b32 s19, s11, 1
	v_or_b32_e32 v176, s20, v10
	s_add_i32 s15, s20, 4
	s_add_i32 s14, s19, 4
	s_add_i32 s24, s19, 8
	s_add_i32 s25, s20, 8
	v_lshlrev_b64 v[32:33], 13, v[176:177]
	v_or_b32_e32 v176, s15, v10
	v_mov_b32_e32 v17, v177
	v_mov_b32_e32 v19, v177
	v_mov_b32_e32 v21, v177
	v_or_b32_e32 v16, s19, v3
	s_add_i32 s26, s19, 12
	s_add_i32 s27, s20, 12
	s_add_i32 s28, s19, 16
	s_add_i32 s30, s19, 20
	s_add_i32 s34, s19, 24
	s_add_i32 s37, s19, 28
	v_or_b32_e32 v18, s14, v3
	v_or_b32_e32 v20, s24, v3
	v_lshlrev_b64 v[34:35], 13, v[176:177]
	v_or_b32_e32 v176, s25, v10
	v_mov_b32_e32 v23, v177
	v_mov_b32_e32 v25, v177
	v_mov_b32_e32 v27, v177
	v_mov_b32_e32 v29, v177
	v_mov_b32_e32 v31, v177
	s_add_i32 s29, s20, 16
	v_lshlrev_b64 v[16:17], 13, v[16:17]
	v_or_b32_e32 v22, s26, v3
	v_or_b32_e32 v24, s28, v3
	v_or_b32_e32 v26, s30, v3
	v_or_b32_e32 v28, s34, v3
	v_or_b32_e32 v30, s37, v3
	v_lshl_add_u64 v[32:33], v[8:9], 0, v[32:33]
	v_lshlrev_b64 v[18:19], 13, v[18:19]
	v_lshlrev_b64 v[20:21], 13, v[20:21]
	v_lshlrev_b64 v[36:37], 13, v[176:177]
	v_or_b32_e32 v176, s27, v10
	s_add_i32 s31, s20, 20
	v_lshl_add_u64 v[16:17], v[8:9], 0, v[16:17]
	v_lshlrev_b64 v[22:23], 13, v[22:23]
	v_lshlrev_b64 v[24:25], 13, v[24:25]
	v_lshlrev_b64 v[26:27], 13, v[26:27]
	v_lshlrev_b64 v[28:29], 13, v[28:29]
	v_lshlrev_b64 v[30:31], 13, v[30:31]
	v_lshl_add_u64 v[34:35], v[8:9], 0, v[34:35]
	v_lshl_add_u64 v[18:19], v[8:9], 0, v[18:19]
	v_lshl_add_u64 v[20:21], v[8:9], 0, v[20:21]
	global_load_dword v48, v[32:33], off nt
	global_load_dword v49, v[16:17], off nt
	v_lshlrev_b64 v[32:33], 13, v[176:177]
	v_or_b32_e32 v176, s29, v10
	s_add_i32 s35, s20, 24
	v_lshl_add_u64 v[22:23], v[8:9], 0, v[22:23]
	v_lshl_add_u64 v[24:25], v[8:9], 0, v[24:25]
	v_lshl_add_u64 v[26:27], v[8:9], 0, v[26:27]
	v_lshl_add_u64 v[28:29], v[8:9], 0, v[28:29]
	v_lshl_add_u64 v[30:31], v[8:9], 0, v[30:31]
	global_load_dword v50, v[34:35], off nt
	global_load_dword v51, v[18:19], off nt
	global_load_dword v52, v[20:21], off nt
	global_load_dword v53, v[22:23], off nt
	global_load_dword v54, v[24:25], off nt
	global_load_dword v55, v[26:27], off nt
	global_load_dword v56, v[28:29], off nt
	global_load_dword v57, v[30:31], off nt
	v_lshl_add_u64 v[18:19], v[8:9], 0, v[32:33]
	v_lshlrev_b64 v[20:21], 13, v[176:177]
	v_or_b32_e32 v176, s31, v10
	s_add_i32 s38, s20, 28
	v_lshl_add_u64 v[16:17], v[8:9], 0, v[36:37]
	global_load_dword v58, v[18:19], off nt
	global_load_dword v59, v[16:17], off nt
	v_lshlrev_b64 v[18:19], 13, v[176:177]
	v_or_b32_e32 v176, s35, v10
	v_lshl_add_u64 v[16:17], v[8:9], 0, v[20:21]
	v_lshlrev_b64 v[20:21], 13, v[176:177]
	v_or_b32_e32 v176, s38, v10
	v_lshlrev_b64 v[22:23], 13, v[176:177]
	v_lshl_add_u64 v[22:23], v[8:9], 0, v[22:23]
	v_lshl_add_u64 v[18:19], v[8:9], 0, v[18:19]
	v_lshl_add_u64 v[20:21], v[8:9], 0, v[20:21]
	global_load_dword v60, v[22:23], off nt
	global_load_dword v61, v[20:21], off nt
	global_load_dword v62, v[18:19], off nt
	global_load_dword v63, v[16:17], off nt
	v_or_b32_e32 v18, s19, v1
	v_or_b32_e32 v16, s20, v2
	s_add_i32 s12, s12, 16
	s_add_i32 s11, s11, 16
	s_add_i32 s13, s13, -16
	v_mad_u64_u32 v[16:17], s[20:21], v16, s49, v[4:5]
	v_mad_u64_u32 v[18:19], s[20:21], v18, s49, v[4:5]
	v_or_b32_e32 v17, s14, v1
	v_or_b32_e32 v19, s15, v2
	v_or_b32_e32 v26, s24, v1
	v_or_b32_e32 v24, s25, v2
	v_or_b32_e32 v30, s26, v1
	v_or_b32_e32 v28, s27, v2
	v_or_b32_e32 v34, s28, v1
	v_or_b32_e32 v32, s29, v2
	v_or_b32_e32 v38, s30, v1
	v_or_b32_e32 v36, s31, v2
	v_or_b32_e32 v42, s34, v1
	v_or_b32_e32 v40, s35, v2
	v_or_b32_e32 v46, s37, v1
	v_or_b32_e32 v44, s38, v2
	s_cmp_lg_u32 s13, 0
	v_mad_u64_u32 v[20:21], s[20:21], v19, s49, v[4:5]
	v_mad_u64_u32 v[22:23], s[20:21], v17, s49, v[4:5]
	v_mad_u64_u32 v[24:25], s[20:21], v24, s49, v[4:5]
	v_mad_u64_u32 v[26:27], s[20:21], v26, s49, v[4:5]
	v_mad_u64_u32 v[28:29], s[20:21], v28, s49, v[4:5]
	v_mad_u64_u32 v[30:31], s[20:21], v30, s49, v[4:5]
	v_mad_u64_u32 v[32:33], s[20:21], v32, s49, v[4:5]
	v_mad_u64_u32 v[34:35], s[20:21], v34, s49, v[4:5]
	v_mad_u64_u32 v[36:37], s[20:21], v36, s49, v[4:5]
	v_mad_u64_u32 v[38:39], s[20:21], v38, s49, v[4:5]
	v_mad_u64_u32 v[40:41], s[20:21], v40, s49, v[4:5]
	v_mad_u64_u32 v[42:43], s[20:21], v42, s49, v[4:5]
	v_mad_u64_u32 v[44:45], s[20:21], v44, s49, v[4:5]
	v_mad_u64_u32 v[46:47], s[20:21], v46, s49, v[4:5]
	s_waitcnt vmcnt(0)
	ds_write_b32 v16, v48
	ds_write_b32 v18, v49
	ds_write_b32 v20, v50
	ds_write_b32 v22, v51
	ds_write_b32 v24, v59
	ds_write_b32 v26, v52
	ds_write_b32 v28, v58
	ds_write_b32 v30, v53
	ds_write_b32 v32, v63
	ds_write_b32 v34, v54
	ds_write_b32 v36, v62
	ds_write_b32 v38, v55
	ds_write_b32 v40, v61
	ds_write_b32 v42, v56
	ds_write_b32 v44, v60
	ds_write_b32 v46, v57
	s_cbranch_scc1 .LBB0_504
; #define LAS __attribute__((address_space(3)))
; __device__ __forceinline__ unsigned cvt_pk_bf16(float lo, float hi) { unsigned r; asm volatile("v_cvt_pk_bf16_f32 %0, %1, %2" : "=v"(r) : "v"(lo), "v"(hi)); return r; }
; __device__ __forceinline__ void transpose_item(const float* W, int K, int N, int NP, int kind, bf16_t* WT, LAS float* scr, int item, int lane) {
;     ...
;     asm volatile("s_waitcnt lgkmcnt(0)" ::: "memory");
;     const int c = lane & 7;
; #pragma unroll
;     for (int j = 0; j < 4; ++j) { const int n = (lane >> 3) + 8 * j; const LAS float* s = scr + (8 * c) * 33 + n;
;         u32x4 o; o.x = cvt_pk_bf16(s[0 * 33], s[1 * 33]); o.y = cvt_pk_bf16(s[2 * 33], s[3 * 33]); o.z = cvt_pk_bf16(s[4 * 33], s[5 * 33]); o.w = cvt_pk_bf16(s[6 * 33], s[7 * 33]);
;         *(u32x4*)(WT + (size_t)(n0 + n) * K + k0 + 8 * c) = o; }
;     asm volatile("s_waitcnt lgkmcnt(0)" ::: "memory");
	s_waitcnt lgkmcnt(0)
	s_lshl_b32 s9, s9, 1
	ds_read2_b32 v[8:9], v11 offset1:33
	s_add_u32 s12, s18, s9
	s_waitcnt lgkmcnt(0)
	v_cvt_pk_bf16_f32 v16, v8, v9
	ds_read2_b32 v[8:9], v11 offset0:66 offset1:99
	v_lshlrev_b32_e32 v176, 1, v6
	s_addc_u32 s13, s4, 0
	s_waitcnt lgkmcnt(0)
	v_cvt_pk_bf16_f32 v17, v8, v9
	ds_read2_b32 v[8:9], v11 offset0:132 offset1:165
	v_or_b32_e32 v3, s8, v7
	v_lshl_add_u64 v[20:21], s[12:13], 0, v[176:177]
	s_mov_b64 s[12:13], 0x3a00000
	s_waitcnt lgkmcnt(0)
	v_cvt_pk_bf16_f32 v18, v8, v9
	ds_read2_b32 v[8:9], v11 offset0:198 offset1:231
	v_lshlrev_b32_e32 v176, 12, v3
	v_lshl_add_u64 v[20:21], v[20:21], 0, s[12:13]
	s_waitcnt lgkmcnt(0)
	v_cvt_pk_bf16_f32 v19, v8, v9
	ds_read2_b32 v[8:9], v11 offset0:8 offset1:41
	v_lshl_add_u64 v[22:23], v[20:21], 0, v[176:177]
	global_store_dwordx4 v[22:23], v[16:19], off
	v_or_b32_e32 v3, s8, v12
	v_lshlrev_b32_e32 v176, 12, v3
	s_waitcnt lgkmcnt(0)
	v_cvt_pk_bf16_f32 v16, v8, v9
	ds_read2_b32 v[8:9], v11 offset0:74 offset1:107
	s_waitcnt lgkmcnt(0)
	v_cvt_pk_bf16_f32 v17, v8, v9
	ds_read2_b32 v[8:9], v11 offset0:140 offset1:173
	s_waitcnt lgkmcnt(0)
	v_cvt_pk_bf16_f32 v18, v8, v9
	ds_read2_b32 v[8:9], v11 offset0:206 offset1:239
	s_waitcnt lgkmcnt(0)
	v_cvt_pk_bf16_f32 v19, v8, v9
	ds_read2_b32 v[8:9], v11 offset0:16 offset1:49
	v_lshl_add_u64 v[22:23], v[20:21], 0, v[176:177]
	global_store_dwordx4 v[22:23], v[16:19], off
	v_or_b32_e32 v3, s8, v13
	v_lshlrev_b32_e32 v176, 12, v3
	s_waitcnt lgkmcnt(0)
	v_cvt_pk_bf16_f32 v16, v8, v9
	ds_read2_b32 v[8:9], v11 offset0:82 offset1:115
	s_waitcnt lgkmcnt(0)
	v_cvt_pk_bf16_f32 v17, v8, v9
	ds_read2_b32 v[8:9], v11 offset0:148 offset1:181
	s_waitcnt lgkmcnt(0)
	v_cvt_pk_bf16_f32 v18, v8, v9
	ds_read2_b32 v[8:9], v11 offset0:214 offset1:247
	s_waitcnt lgkmcnt(0)
	v_cvt_pk_bf16_f32 v19, v8, v9
	ds_read2_b32 v[8:9], v11 offset0:24 offset1:57
	v_lshl_add_u64 v[22:23], v[20:21], 0, v[176:177]
	global_store_dwordx4 v[22:23], v[16:19], off
	v_or_b32_e32 v3, s8, v14
	v_lshlrev_b32_e32 v176, 12, v3
	s_waitcnt lgkmcnt(0)
	v_cvt_pk_bf16_f32 v16, v8, v9
	ds_read2_b32 v[8:9], v11 offset0:90 offset1:123
	s_waitcnt lgkmcnt(0)
	v_cvt_pk_bf16_f32 v17, v8, v9
	ds_read2_b32 v[8:9], v11 offset0:156 offset1:189
	s_waitcnt lgkmcnt(0)
	v_cvt_pk_bf16_f32 v18, v8, v9
	ds_read2_b32 v[8:9], v11 offset0:222 offset1:255
	s_waitcnt lgkmcnt(0)
	v_cvt_pk_bf16_f32 v19, v8, v9
	v_lshl_add_u64 v[8:9], v[20:21], 0, v[176:177]
	global_store_dwordx4 v[8:9], v[16:19], off
	s_waitcnt lgkmcnt(0)
	s_mov_b64 s[38:39], 0x800
	s_mov_b32 s64, s16

; #define LAS __attribute__((address_space(3)))
; __device__ __forceinline__ void transpose_item(const float* W, int K, int N, int NP, int kind, bf16_t* WT, LAS float* scr, int item, int lane) {
;     const int nblk = NP / 32, kb = item / nblk, nb = item % nblk, k0 = 64 * kb, n0 = 32 * nb;
;     bool rp; const int sb = src_group_base(kind, n0, rp);
;     const int p = lane & 31; const int so = rp ? (4 * (p >> 3) + (p & 3) + 16 * ((p >> 2) & 1)) : p;
; #pragma unroll 8
;     for (int i = 0; i < 32; ++i) { const int kk = 2 * i + (lane >> 5); scr[kk * 33 + p] = W[(size_t)(k0 + kk) * N + sb + so]; }
.LBB0_509:
	s_lshl_b32 s19, s11, 1
	s_lshl_b32 s13, s9, 1
	v_or_b32_e32 v176, s19, v10
	s_add_i32 s15, s19, 4
	s_add_i32 s14, s13, 4
	s_add_i32 s24, s13, 8
	s_add_i32 s25, s19, 8
	v_lshlrev_b64 v[32:33], 13, v[176:177]
	v_or_b32_e32 v176, s15, v10
	v_mov_b32_e32 v17, v177
	v_mov_b32_e32 v19, v177
	v_mov_b32_e32 v21, v177
	v_or_b32_e32 v16, s13, v3
	s_add_i32 s26, s13, 12
	s_add_i32 s27, s19, 12
	s_add_i32 s28, s13, 16
	s_add_i32 s30, s13, 20
	s_add_i32 s34, s13, 24
	s_add_i32 s37, s13, 28
	v_or_b32_e32 v18, s14, v3
	v_or_b32_e32 v20, s24, v3
	v_lshlrev_b64 v[34:35], 13, v[176:177]
	v_or_b32_e32 v176, s25, v10
	v_mov_b32_e32 v23, v177
	v_mov_b32_e32 v25, v177
	v_mov_b32_e32 v27, v177
	v_mov_b32_e32 v29, v177
	v_mov_b32_e32 v31, v177
	s_add_i32 s29, s19, 16
	v_lshlrev_b64 v[16:17], 13, v[16:17]
	v_or_b32_e32 v22, s26, v3
	v_or_b32_e32 v24, s28, v3
	v_or_b32_e32 v26, s30, v3
	v_or_b32_e32 v28, s34, v3
	v_or_b32_e32 v30, s37, v3
	v_lshl_add_u64 v[32:33], v[8:9], 0, v[32:33]
	v_lshlrev_b64 v[18:19], 13, v[18:19]
	v_lshlrev_b64 v[20:21], 13, v[20:21]
	v_lshlrev_b64 v[36:37], 13, v[176:177]
	v_or_b32_e32 v176, s27, v10
	s_add_i32 s31, s19, 20
	v_lshl_add_u64 v[16:17], v[8:9], 0, v[16:17]
	v_lshlrev_b64 v[22:23], 13, v[22:23]
	v_lshlrev_b64 v[24:25], 13, v[24:25]
	v_lshlrev_b64 v[26:27], 13, v[26:27]
	v_lshlrev_b64 v[28:29], 13, v[28:29]
	v_lshlrev_b64 v[30:31], 13, v[30:31]
	v_lshl_add_u64 v[34:35], v[8:9], 0, v[34:35]
	v_lshl_add_u64 v[18:19], v[8:9], 0, v[18:19]
	v_lshl_add_u64 v[20:21], v[8:9], 0, v[20:21]
	global_load_dword v48, v[32:33], off nt
	global_load_dword v49, v[16:17], off nt
	v_lshlrev_b64 v[32:33], 13, v[176:177]
	v_or_b32_e32 v176, s29, v10
	s_add_i32 s35, s19, 24
	v_lshl_add_u64 v[22:23], v[8:9], 0, v[22:23]
	v_lshl_add_u64 v[24:25], v[8:9], 0, v[24:25]
	v_lshl_add_u64 v[26:27], v[8:9], 0, v[26:27]
	v_lshl_add_u64 v[28:29], v[8:9], 0, v[28:29]
	v_lshl_add_u64 v[30:31], v[8:9], 0, v[30:31]
	global_load_dword v50, v[34:35], off nt
	global_load_dword v51, v[18:19], off nt
	global_load_dword v52, v[20:21], off nt
	global_load_dword v53, v[22:23], off nt
	global_load_dword v54, v[24:25], off nt
	global_load_dword v55, v[26:27], off nt
	global_load_dword v56, v[28:29], off nt
	global_load_dword v57, v[30:31], off nt
	v_lshl_add_u64 v[18:19], v[8:9], 0, v[32:33]
	v_lshlrev_b64 v[20:21], 13, v[176:177]
	v_or_b32_e32 v176, s31, v10
	s_add_i32 s38, s19, 28
	v_lshl_add_u64 v[16:17], v[8:9], 0, v[36:37]
	global_load_dword v58, v[18:19], off nt
	global_load_dword v59, v[16:17], off nt
	v_lshlrev_b64 v[18:19], 13, v[176:177]
	v_or_b32_e32 v176, s35, v10
	v_lshl_add_u64 v[16:17], v[8:9], 0, v[20:21]
	v_lshlrev_b64 v[20:21], 13, v[176:177]
	v_or_b32_e32 v176, s38, v10
	v_lshlrev_b64 v[22:23], 13, v[176:177]
	v_lshl_add_u64 v[22:23], v[8:9], 0, v[22:23]
	v_lshl_add_u64 v[18:19], v[8:9], 0, v[18:19]
	v_lshl_add_u64 v[20:21], v[8:9], 0, v[20:21]
	global_load_dword v60, v[22:23], off nt
	global_load_dword v61, v[20:21], off nt
	global_load_dword v62, v[18:19], off nt
	global_load_dword v63, v[16:17], off nt
	v_or_b32_e32 v18, s13, v1
	v_or_b32_e32 v16, s19, v2
	s_add_i32 s11, s11, 16
	s_add_i32 s9, s9, 16
	s_add_i32 s12, s12, -16
	v_mad_u64_u32 v[16:17], s[20:21], v16, s49, v[4:5]
	v_mad_u64_u32 v[18:19], s[20:21], v18, s49, v[4:5]
	v_or_b32_e32 v17, s14, v1
	v_or_b32_e32 v19, s15, v2
	v_or_b32_e32 v26, s24, v1
	v_or_b32_e32 v24, s25, v2
	v_or_b32_e32 v30, s26, v1
	v_or_b32_e32 v28, s27, v2
	v_or_b32_e32 v34, s28, v1
	v_or_b32_e32 v32, s29, v2
	v_or_b32_e32 v38, s30, v1
	v_or_b32_e32 v36, s31, v2
	v_or_b32_e32 v42, s34, v1
	v_or_b32_e32 v40, s35, v2
	v_or_b32_e32 v46, s37, v1
	v_or_b32_e32 v44, s38, v2
	s_cmp_lg_u32 s12, 0
	v_mad_u64_u32 v[20:21], s[20:21], v19, s49, v[4:5]
	v_mad_u64_u32 v[22:23], s[20:21], v17, s49, v[4:5]
	v_mad_u64_u32 v[24:25], s[20:21], v24, s49, v[4:5]
	v_mad_u64_u32 v[26:27], s[20:21], v26, s49, v[4:5]
	v_mad_u64_u32 v[28:29], s[20:21], v28, s49, v[4:5]
	v_mad_u64_u32 v[30:31], s[20:21], v30, s49, v[4:5]
	v_mad_u64_u32 v[32:33], s[20:21], v32, s49, v[4:5]
	v_mad_u64_u32 v[34:35], s[20:21], v34, s49, v[4:5]
	v_mad_u64_u32 v[36:37], s[20:21], v36, s49, v[4:5]
	v_mad_u64_u32 v[38:39], s[20:21], v38, s49, v[4:5]
	v_mad_u64_u32 v[40:41], s[20:21], v40, s49, v[4:5]
	v_mad_u64_u32 v[42:43], s[20:21], v42, s49, v[4:5]
	v_mad_u64_u32 v[44:45], s[20:21], v44, s49, v[4:5]
	v_mad_u64_u32 v[46:47], s[20:21], v46, s49, v[4:5]
	s_waitcnt vmcnt(0)
	ds_write_b32 v16, v48
	ds_write_b32 v18, v49
	ds_write_b32 v20, v50
	ds_write_b32 v22, v51
	ds_write_b32 v24, v59
	ds_write_b32 v26, v52
	ds_write_b32 v28, v58
	ds_write_b32 v30, v53
	ds_write_b32 v32, v63
	ds_write_b32 v34, v54
	ds_write_b32 v36, v62
	ds_write_b32 v38, v55
	ds_write_b32 v40, v61
	ds_write_b32 v42, v56
	ds_write_b32 v44, v60
	ds_write_b32 v46, v57
	s_cbranch_scc1 .LBB0_509
; #define LAS __attribute__((address_space(3)))
; __device__ __forceinline__ unsigned cvt_pk_bf16(float lo, float hi) { unsigned r; asm volatile("v_cvt_pk_bf16_f32 %0, %1, %2" : "=v"(r) : "v"(lo), "v"(hi)); return r; }
; __device__ __forceinline__ void transpose_item(const float* W, int K, int N, int NP, int kind, bf16_t* WT, LAS float* scr, int item, int lane) {
;     ...
;     asm volatile("s_waitcnt lgkmcnt(0)" ::: "memory");
;     const int c = lane & 7;
; #pragma unroll
;     for (int j = 0; j < 4; ++j) { const int n = (lane >> 3) + 8 * j; const LAS float* s = scr + (8 * c) * 33 + n;
;         u32x4 o; o.x = cvt_pk_bf16(s[0 * 33], s[1 * 33]); o.y = cvt_pk_bf16(s[2 * 33], s[3 * 33]); o.z = cvt_pk_bf16(s[4 * 33], s[5 * 33]); o.w = cvt_pk_bf16(s[6 * 33], s[7 * 33]);
;         *(u32x4*)(WT + (size_t)(n0 + n) * K + k0 + 8 * c) = o; }
;     asm volatile("s_waitcnt lgkmcnt(0)" ::: "memory");
	s_waitcnt lgkmcnt(0)
	s_lshl_b32 s8, s8, 1
	ds_read2_b32 v[8:9], v11 offset1:33
	s_add_u32 s8, s18, s8
	s_waitcnt lgkmcnt(0)
	v_cvt_pk_bf16_f32 v16, v8, v9
	ds_read2_b32 v[8:9], v11 offset0:66 offset1:99
	v_lshlrev_b32_e32 v176, 1, v6
	s_addc_u32 s9, s4, 0
	s_waitcnt lgkmcnt(0)
	v_cvt_pk_bf16_f32 v17, v8, v9
	ds_read2_b32 v[8:9], v11 offset0:132 offset1:165
	v_or_b32_e32 v3, s1, v7
	v_lshl_add_u64 v[20:21], s[8:9], 0, v[176:177]
	s_mov_b64 s[8:9], 0x3200000
	s_waitcnt lgkmcnt(0)
	v_cvt_pk_bf16_f32 v18, v8, v9
	ds_read2_b32 v[8:9], v11 offset0:198 offset1:231
	v_lshlrev_b32_e32 v176, 12, v3
	v_lshl_add_u64 v[20:21], v[20:21], 0, s[8:9]
	s_waitcnt lgkmcnt(0)
	v_cvt_pk_bf16_f32 v19, v8, v9
	ds_read2_b32 v[8:9], v11 offset0:8 offset1:41
	v_lshl_add_u64 v[22:23], v[20:21], 0, v[176:177]
	global_store_dwordx4 v[22:23], v[16:19], off
	v_or_b32_e32 v3, s1, v12
	v_lshlrev_b32_e32 v176, 12, v3
	s_waitcnt lgkmcnt(0)
	v_cvt_pk_bf16_f32 v16, v8, v9
	ds_read2_b32 v[8:9], v11 offset0:74 offset1:107
	s_waitcnt lgkmcnt(0)
	v_cvt_pk_bf16_f32 v17, v8, v9
	ds_read2_b32 v[8:9], v11 offset0:140 offset1:173
	s_waitcnt lgkmcnt(0)
	v_cvt_pk_bf16_f32 v18, v8, v9
	ds_read2_b32 v[8:9], v11 offset0:206 offset1:239
	s_waitcnt lgkmcnt(0)
	v_cvt_pk_bf16_f32 v19, v8, v9
	ds_read2_b32 v[8:9], v11 offset0:16 offset1:49
	v_lshl_add_u64 v[22:23], v[20:21], 0, v[176:177]
	global_store_dwordx4 v[22:23], v[16:19], off
	v_or_b32_e32 v3, s1, v13
	v_lshlrev_b32_e32 v176, 12, v3
	s_waitcnt lgkmcnt(0)
	v_cvt_pk_bf16_f32 v16, v8, v9
	ds_read2_b32 v[8:9], v11 offset0:82 offset1:115
	s_waitcnt lgkmcnt(0)
	v_cvt_pk_bf16_f32 v17, v8, v9
	ds_read2_b32 v[8:9], v11 offset0:148 offset1:181
	s_waitcnt lgkmcnt(0)
	v_cvt_pk_bf16_f32 v18, v8, v9
	ds_read2_b32 v[8:9], v11 offset0:214 offset1:247
	s_waitcnt lgkmcnt(0)
	v_cvt_pk_bf16_f32 v19, v8, v9
	ds_read2_b32 v[8:9], v11 offset0:24 offset1:57
	v_lshl_add_u64 v[22:23], v[20:21], 0, v[176:177]
	global_store_dwordx4 v[22:23], v[16:19], off
	v_or_b32_e32 v3, s1, v14
	v_lshlrev_b32_e32 v176, 12, v3
	s_waitcnt lgkmcnt(0)
	v_cvt_pk_bf16_f32 v16, v8, v9
	ds_read2_b32 v[8:9], v11 offset0:90 offset1:123
	s_waitcnt lgkmcnt(0)
	v_cvt_pk_bf16_f32 v17, v8, v9
	ds_read2_b32 v[8:9], v11 offset0:156 offset1:189
	s_waitcnt lgkmcnt(0)
	v_cvt_pk_bf16_f32 v18, v8, v9
	ds_read2_b32 v[8:9], v11 offset0:222 offset1:255
	s_waitcnt lgkmcnt(0)
	v_cvt_pk_bf16_f32 v19, v8, v9
	v_lshl_add_u64 v[8:9], v[20:21], 0, v[176:177]
	global_store_dwordx4 v[8:9], v[16:19], off
	s_waitcnt lgkmcnt(0)
	s_mov_b64 s[38:39], 0x800
	s_mov_b32 s64, s16

; #define LAS __attribute__((address_space(3)))
; __device__ __forceinline__ unsigned cvt_pk_bf16(float lo, float hi) { unsigned r; asm volatile("v_cvt_pk_bf16_f32 %0, %1, %2" : "=v"(r) : "v"(lo), "v"(hi)); return r; }
; __device__ __forceinline__ void transpose_item(const float* W, int K, int N, int NP, int kind, bf16_t* WT, LAS float* scr, int item, int lane) {
;     const int nblk = NP / 32, kb = item / nblk, nb = item % nblk, k0 = 64 * kb, n0 = 32 * nb;
;     bool rp; const int sb = src_group_base(kind, n0, rp);
;     const int p = lane & 31; const int so = rp ? (4 * (p >> 3) + (p & 3) + 16 * ((p >> 2) & 1)) : p;
; #pragma unroll 8
;     for (int i = 0; i < 32; ++i) { const int kk = 2 * i + (lane >> 5); scr[kk * 33 + p] = W[(size_t)(k0 + kk) * N + sb + so]; }
;     asm volatile("s_waitcnt lgkmcnt(0)" ::: "memory");
;     const int c = lane & 7;
; #pragma unroll
;     for (int j = 0; j < 4; ++j) { const int n = (lane >> 3) + 8 * j; const LAS float* s = scr + (8 * c) * 33 + n;
;         u32x4 o; o.x = cvt_pk_bf16(s[0 * 33], s[1 * 33]); o.y = cvt_pk_bf16(s[2 * 33], s[3 * 33]); o.z = cvt_pk_bf16(s[4 * 33], s[5 * 33]); o.w = cvt_pk_bf16(s[6 * 33], s[7 * 33]);
;         *(u32x4*)(WT + (size_t)(n0 + n) * K + k0 + 8 * c) = o; }
;     asm volatile("s_waitcnt lgkmcnt(0)" ::: "memory");
.LBB0_525:
	s_lshl_b32 s12, s1, 1
	s_lshl_b32 s13, s8, 1
	v_or_b32_e32 v16, s13, v10
	s_add_i32 s14, s12, 4
	s_add_i32 s15, s13, 4
	s_add_i32 s20, s12, 8
	s_add_i32 s21, s13, 8
	s_add_i32 s24, s12, 12
	s_add_i32 s25, s13, 12
	s_add_i32 s26, s12, 16
	s_add_i32 s27, s13, 16
	s_add_i32 s28, s12, 20
	s_add_i32 s29, s13, 20
	s_add_i32 s30, s12, 24
	s_add_i32 s31, s13, 24
	s_add_i32 s34, s12, 28
	s_add_i32 s35, s13, 28
	v_or_b32_e32 v18, s12, v3
	v_mad_i64_i32 v[16:17], s[10:11], v16, s36, v[8:9]
	v_or_b32_e32 v22, s14, v3
	v_or_b32_e32 v20, s15, v10
	v_or_b32_e32 v26, s20, v3
	v_or_b32_e32 v24, s21, v10
	v_or_b32_e32 v30, s24, v3
	v_or_b32_e32 v28, s25, v10
	v_or_b32_e32 v34, s26, v3
	v_or_b32_e32 v32, s27, v10
	v_or_b32_e32 v38, s28, v3
	v_or_b32_e32 v36, s29, v10
	v_or_b32_e32 v42, s30, v3
	v_or_b32_e32 v40, s31, v10
	v_or_b32_e32 v46, s34, v3
	v_or_b32_e32 v44, s35, v10
	v_mad_i64_i32 v[18:19], s[10:11], v18, s36, v[8:9]
	v_mad_i64_i32 v[20:21], s[10:11], v20, s36, v[8:9]
	v_mad_i64_i32 v[22:23], s[10:11], v22, s36, v[8:9]
	v_mad_i64_i32 v[24:25], s[10:11], v24, s36, v[8:9]
	v_mad_i64_i32 v[26:27], s[10:11], v26, s36, v[8:9]
	v_mad_i64_i32 v[28:29], s[10:11], v28, s36, v[8:9]
	v_mad_i64_i32 v[30:31], s[10:11], v30, s36, v[8:9]
	v_mad_i64_i32 v[32:33], s[10:11], v32, s36, v[8:9]
	v_mad_i64_i32 v[34:35], s[10:11], v34, s36, v[8:9]
	v_mad_i64_i32 v[36:37], s[10:11], v36, s36, v[8:9]
	v_mad_i64_i32 v[38:39], s[10:11], v38, s36, v[8:9]
	v_mad_i64_i32 v[40:41], s[10:11], v40, s36, v[8:9]
	v_mad_i64_i32 v[42:43], s[10:11], v42, s36, v[8:9]
	v_mad_i64_i32 v[44:45], s[10:11], v44, s36, v[8:9]
	v_mad_i64_i32 v[46:47], s[10:11], v46, s36, v[8:9]
	global_load_dword v48, v[16:17], off nt
	global_load_dword v49, v[18:19], off nt
	global_load_dword v50, v[20:21], off nt
	global_load_dword v51, v[22:23], off nt
	global_load_dword v52, v[24:25], off nt
	global_load_dword v53, v[26:27], off nt
	global_load_dword v54, v[28:29], off nt
	global_load_dword v55, v[30:31], off nt
	global_load_dword v56, v[32:33], off nt
	global_load_dword v57, v[34:35], off nt
	global_load_dword v58, v[36:37], off nt
	global_load_dword v59, v[38:39], off nt
	global_load_dword v60, v[40:41], off nt
	global_load_dword v61, v[42:43], off nt
	global_load_dword v62, v[44:45], off nt
	global_load_dword v63, v[46:47], off nt
	v_or_b32_e32 v18, s12, v1
	v_or_b32_e32 v16, s13, v2
	s_add_i32 s8, s8, 16
	s_add_i32 s1, s1, 16
	s_add_i32 s9, s9, -16
	v_mad_u64_u32 v[16:17], s[10:11], v16, s49, v[4:5]
	v_mad_u64_u32 v[18:19], s[10:11], v18, s49, v[4:5]
	v_or_b32_e32 v17, s14, v1
	v_or_b32_e32 v19, s15, v2
	v_or_b32_e32 v26, s20, v1
	v_or_b32_e32 v24, s21, v2
	v_or_b32_e32 v30, s24, v1
	v_or_b32_e32 v28, s25, v2
	v_or_b32_e32 v34, s26, v1
	v_or_b32_e32 v32, s27, v2
	v_or_b32_e32 v38, s28, v1
	v_or_b32_e32 v36, s29, v2
	v_or_b32_e32 v42, s30, v1
	v_or_b32_e32 v40, s31, v2
	v_or_b32_e32 v46, s34, v1
	v_or_b32_e32 v44, s35, v2
	s_cmp_lg_u32 s9, 0
	v_mad_u64_u32 v[20:21], s[10:11], v19, s49, v[4:5]
	v_mad_u64_u32 v[22:23], s[10:11], v17, s49, v[4:5]
	v_mad_u64_u32 v[24:25], s[10:11], v24, s49, v[4:5]
	v_mad_u64_u32 v[26:27], s[10:11], v26, s49, v[4:5]
	v_mad_u64_u32 v[28:29], s[10:11], v28, s49, v[4:5]
	v_mad_u64_u32 v[30:31], s[10:11], v30, s49, v[4:5]
	v_mad_u64_u32 v[32:33], s[10:11], v32, s49, v[4:5]
	v_mad_u64_u32 v[34:35], s[10:11], v34, s49, v[4:5]
	v_mad_u64_u32 v[36:37], s[10:11], v36, s49, v[4:5]
	v_mad_u64_u32 v[38:39], s[10:11], v38, s49, v[4:5]
	v_mad_u64_u32 v[40:41], s[10:11], v40, s49, v[4:5]
	v_mad_u64_u32 v[42:43], s[10:11], v42, s49, v[4:5]
	v_mad_u64_u32 v[44:45], s[10:11], v44, s49, v[4:5]
	v_mad_u64_u32 v[46:47], s[10:11], v46, s49, v[4:5]
	s_waitcnt vmcnt(0)
	ds_write_b32 v16, v48
	ds_write_b32 v18, v49
	ds_write_b32 v20, v50
	ds_write_b32 v22, v51
	ds_write_b32 v24, v52
	ds_write_b32 v26, v53
	ds_write_b32 v28, v54
	ds_write_b32 v30, v55
	ds_write_b32 v32, v56
	ds_write_b32 v34, v57
	ds_write_b32 v36, v58
	ds_write_b32 v38, v59
	ds_write_b32 v40, v60
	ds_write_b32 v42, v61
	ds_write_b32 v44, v62
	ds_write_b32 v46, v63
	s_cbranch_scc1 .LBB0_525
	s_waitcnt lgkmcnt(0)
	s_ashr_i32 s1, s0, 31
	ds_read2_b32 v[8:9], v11 offset1:33
	s_lshl_b64 s[0:1], s[0:1], 1
	s_waitcnt lgkmcnt(0)
	v_cvt_pk_bf16_f32 v16, v8, v9
	ds_read2_b32 v[8:9], v11 offset0:66 offset1:99
	v_or_b32_e32 v20, s19, v7
	s_add_u32 s0, s18, s0
	s_waitcnt lgkmcnt(0)
	v_cvt_pk_bf16_f32 v17, v8, v9
	ds_read2_b32 v[8:9], v11 offset0:132 offset1:165
	v_lshlrev_b32_e32 v176, 1, v6
	v_ashrrev_i32_e32 v21, 31, v20
	s_addc_u32 s1, s4, s1
	s_waitcnt lgkmcnt(0)
	v_cvt_pk_bf16_f32 v18, v8, v9
	ds_read2_b32 v[8:9], v11 offset0:198 offset1:231
	v_lshlrev_b64 v[20:21], 12, v[20:21]
	v_lshl_add_u64 v[22:23], s[0:1], 0, v[176:177]
	s_waitcnt lgkmcnt(0)
	v_cvt_pk_bf16_f32 v19, v8, v9
	ds_read2_b32 v[8:9], v11 offset0:8 offset1:41
	v_lshl_add_u64 v[20:21], v[22:23], 0, v[20:21]
	global_store_dwordx4 v[20:21], v[16:19], off
	v_or_b32_e32 v20, s19, v12
	v_ashrrev_i32_e32 v21, 31, v20
	s_waitcnt lgkmcnt(0)
	v_cvt_pk_bf16_f32 v16, v8, v9
	ds_read2_b32 v[8:9], v11 offset0:74 offset1:107
	s_waitcnt lgkmcnt(0)
	v_cvt_pk_bf16_f32 v17, v8, v9
	ds_read2_b32 v[8:9], v11 offset0:140 offset1:173
	s_waitcnt lgkmcnt(0)
	v_cvt_pk_bf16_f32 v18, v8, v9
	ds_read2_b32 v[8:9], v11 offset0:206 offset1:239
	v_lshlrev_b64 v[20:21], 12, v[20:21]
	s_waitcnt lgkmcnt(0)
	v_cvt_pk_bf16_f32 v19, v8, v9
	ds_read2_b32 v[8:9], v11 offset0:16 offset1:49
	v_lshl_add_u64 v[20:21], v[22:23], 0, v[20:21]
	global_store_dwordx4 v[20:21], v[16:19], off
	v_or_b32_e32 v20, s19, v13
	v_ashrrev_i32_e32 v21, 31, v20
	s_waitcnt lgkmcnt(0)
	v_cvt_pk_bf16_f32 v16, v8, v9
	ds_read2_b32 v[8:9], v11 offset0:82 offset1:115
	s_waitcnt lgkmcnt(0)
	v_cvt_pk_bf16_f32 v17, v8, v9
	ds_read2_b32 v[8:9], v11 offset0:148 offset1:181
	s_waitcnt lgkmcnt(0)
	v_cvt_pk_bf16_f32 v18, v8, v9
	ds_read2_b32 v[8:9], v11 offset0:214 offset1:247
	v_lshlrev_b64 v[20:21], 12, v[20:21]
	s_waitcnt lgkmcnt(0)
	v_cvt_pk_bf16_f32 v19, v8, v9
	ds_read2_b32 v[8:9], v11 offset0:24 offset1:57
	v_lshl_add_u64 v[20:21], v[22:23], 0, v[20:21]
	global_store_dwordx4 v[20:21], v[16:19], off
	v_or_b32_e32 v20, s19, v14
	v_ashrrev_i32_e32 v21, 31, v20
	s_waitcnt lgkmcnt(0)
	v_cvt_pk_bf16_f32 v16, v8, v9
	ds_read2_b32 v[8:9], v11 offset0:90 offset1:123
	s_waitcnt lgkmcnt(0)
	v_cvt_pk_bf16_f32 v17, v8, v9
	ds_read2_b32 v[8:9], v11 offset0:156 offset1:189
	s_waitcnt lgkmcnt(0)
	v_cvt_pk_bf16_f32 v18, v8, v9
	ds_read2_b32 v[8:9], v11 offset0:222 offset1:255
	v_lshlrev_b64 v[20:21], 12, v[20:21]
	s_waitcnt lgkmcnt(0)
	v_cvt_pk_bf16_f32 v19, v8, v9
	v_lshl_add_u64 v[8:9], v[22:23], 0, v[20:21]
	global_store_dwordx4 v[8:9], v[16:19], off
	s_waitcnt lgkmcnt(0)
	s_mov_b32 s64, s16
	s_branch .LBB0_482

; __global__ void __launch_bounds__(512, 2) fwd_kernel(const Args a) {
;     ...
;             for (int i = tid; i < 3 * 2048; i += 512) { const int v = i >> 11, k = i & 2047; const float cv = v < 2 ? c_in[v * 2048 + k] : cctx_in[k]; sl[i] = cv / (1.0f + __expf(-cv)); }
.LBB0_529:
	v_and_b32_e32 v4, 0x7ff, v3
	v_lshlrev_b32_e32 v176, 2, v4
	v_lshl_add_u64 v[6:7], s[18:19], 0, v[176:177]
	v_cmp_gt_i32_e32 vcc, s4, v3
	s_movk_i32 s2, 0x15ff
	s_nop 0
	v_cndmask_b32_e32 v7, v7, v1, vcc
	v_cndmask_b32_e32 v6, v6, v0, vcc
	global_load_dword v4, v[6:7], off nt
	v_add_u32_e32 v6, 0x200, v3
	v_cmp_lt_i32_e32 vcc, s2, v3
	v_mov_b32_e32 v3, v6
	s_or_b64 s[8:9], vcc, s[8:9]
	v_lshl_add_u64 v[0:1], v[0:1], 0, s[38:39]
	s_waitcnt vmcnt(0)
	v_mul_f32_e32 v6, 0xbfb8aa3b, v4
	v_exp_f32_e32 v6, v6
	s_nop 0
	v_add_f32_e32 v6, 1.0, v6
	v_div_scale_f32 v7, s[10:11], v6, v6, v4
	v_rcp_f32_e32 v8, v7
	v_div_scale_f32 v9, vcc, v4, v6, v4
	v_fma_f32 v10, -v7, v8, 1.0
	v_fmac_f32_e32 v8, v10, v8
	v_mul_f32_e32 v10, v9, v8
	v_fma_f32 v11, -v7, v10, v9
	v_fmac_f32_e32 v10, v11, v8
	v_fma_f32 v7, -v7, v10, v9
	v_div_fmas_f32 v7, v7, v8, v10
	v_div_fixup_f32 v4, v7, v6, v4
	ds_write_b32 v2, v4
	v_add_u32_e32 v2, 0x800, v2
	s_andn2_b64 exec, exec, s[8:9]
	s_cbranch_execnz .LBB0_529

; __global__ void __launch_bounds__(512, 2) fwd_kernel(const Args a) {
;     ...
;             for (int it = bx; it < DEPTH * 192; it += G) {
;                 const int l = it / 192, j0 = (it % 192) * 64;
;                 const float* wp = ada_w + (size_t)l * D * 12288 + (size_t)(wave * 256) * 12288 + j0 + lane;
;                 float a0 = 0.f, a1 = 0.f, a2 = 0.f;
; #pragma unroll 8
;                 for (int k = 0; k < 256; ++k) { const float w = wp[(size_t)k * 12288]; const int kk = wave * 256 + k; a0 += sl[kk] * w; a1 += sl[2048 + kk] * w; a2 += sl[4096 + kk] * w; }
.LBB0_533:
	s_mul_hi_i32 s0, s2, 0x2aaaaaab
	s_lshr_b32 s1, s0, 31
	s_ashr_i32 s4, s0, 5
	s_add_i32 s4, s4, s1
	s_mul_i32 s0, s4, 0xc0
	s_sub_i32 s0, s2, s0
	s_lshl_b32 s8, s0, 6
	s_mul_i32 s1, s4, 0x6000000
	s_mul_hi_i32 s0, s4, 0x6000000
	s_add_u32 s10, s45, s1
	s_addc_u32 s11, s53, s0
	s_ashr_i32 s9, s8, 31
	s_lshl_b64 s[0:1], s[8:9], 2
	s_add_u32 s0, s10, s0
	s_addc_u32 s1, s11, s1
	v_mov_b32_e32 v7, 0
	v_lshl_add_u64 v[2:3], s[0:1], 0, v[176:177]
	s_mov_b64 s[10:11], 0
	s_mov_b32 s9, s60
	v_mov_b32_e32 v4, 0
	v_mov_b32_e32 v5, v7
	v_mov_b32_e32 v28, s60
	s_mov_b32 s10, 7
	global_load_dword v32, v176, s[0:1] nt
	s_add_u32 s0, s0, 0xc000
	s_addc_u32 s1, s1, 0
	global_load_dword v33, v176, s[0:1] nt
	s_add_u32 s0, s0, 0xc000
	s_addc_u32 s1, s1, 0
	global_load_dword v34, v176, s[0:1] nt
	s_add_u32 s0, s0, 0xc000
	s_addc_u32 s1, s1, 0
	global_load_dword v35, v176, s[0:1] nt
	s_add_u32 s0, s0, 0xc000
	s_addc_u32 s1, s1, 0
	global_load_dword v36, v176, s[0:1] nt
	s_add_u32 s0, s0, 0xc000
	s_addc_u32 s1, s1, 0
	global_load_dword v37, v176, s[0:1] nt
	s_add_u32 s0, s0, 0xc000
	s_addc_u32 s1, s1, 0
	global_load_dword v38, v176, s[0:1] nt
	s_add_u32 s0, s0, 0xc000
	s_addc_u32 s1, s1, 0
	global_load_dword v39, v176, s[0:1] nt
	s_add_u32 s0, s0, 0xc000
	s_addc_u32 s1, s1, 0
	global_load_dword v40, v176, s[0:1] nt
	s_add_u32 s0, s0, 0xc000
	s_addc_u32 s1, s1, 0
	global_load_dword v41, v176, s[0:1] nt
	s_add_u32 s0, s0, 0xc000
	s_addc_u32 s1, s1, 0
	global_load_dword v42, v176, s[0:1] nt
	s_add_u32 s0, s0, 0xc000
	s_addc_u32 s1, s1, 0
	global_load_dword v43, v176, s[0:1] nt
	s_add_u32 s0, s0, 0xc000
	s_addc_u32 s1, s1, 0
	global_load_dword v44, v176, s[0:1] nt
	s_add_u32 s0, s0, 0xc000
	s_addc_u32 s1, s1, 0
	global_load_dword v45, v176, s[0:1] nt
	s_add_u32 s0, s0, 0xc000
	s_addc_u32 s1, s1, 0
	global_load_dword v46, v176, s[0:1] nt
	s_add_u32 s0, s0, 0xc000
	s_addc_u32 s1, s1, 0
	global_load_dword v47, v176, s[0:1] nt
	s_add_u32 s0, s0, 0xc000
	s_addc_u32 s1, s1, 0
.Lada_loop:
	global_load_dword v64, v176, s[0:1] nt
	s_add_u32 s0, s0, 0xc000
	s_addc_u32 s1, s1, 0
	global_load_dword v65, v176, s[0:1] nt
	s_add_u32 s0, s0, 0xc000
	s_addc_u32 s1, s1, 0
	global_load_dword v66, v176, s[0:1] nt
	s_add_u32 s0, s0, 0xc000
	s_addc_u32 s1, s1, 0
	global_load_dword v67, v176, s[0:1] nt
	s_add_u32 s0, s0, 0xc000
	s_addc_u32 s1, s1, 0
	global_load_dword v68, v176, s[0:1] nt
	s_add_u32 s0, s0, 0xc000
	s_addc_u32 s1, s1, 0
	global_load_dword v69, v176, s[0:1] nt
	s_add_u32 s0, s0, 0xc000
	s_addc_u32 s1, s1, 0
	global_load_dword v70, v176, s[0:1] nt
	s_add_u32 s0, s0, 0xc000
	s_addc_u32 s1, s1, 0
	global_load_dword v71, v176, s[0:1] nt
	s_add_u32 s0, s0, 0xc000
	s_addc_u32 s1, s1, 0
	global_load_dword v72, v176, s[0:1] nt
	s_add_u32 s0, s0, 0xc000
	s_addc_u32 s1, s1, 0
	global_load_dword v73, v176, s[0:1] nt
	s_add_u32 s0, s0, 0xc000
	s_addc_u32 s1, s1, 0
	global_load_dword v74, v176, s[0:1] nt
	s_add_u32 s0, s0, 0xc000
	s_addc_u32 s1, s1, 0
	global_load_dword v75, v176, s[0:1] nt
	s_add_u32 s0, s0, 0xc000
	s_addc_u32 s1, s1, 0
	global_load_dword v76, v176, s[0:1] nt
	s_add_u32 s0, s0, 0xc000
	s_addc_u32 s1, s1, 0
	global_load_dword v77, v176, s[0:1] nt
	s_add_u32 s0, s0, 0xc000
	s_addc_u32 s1, s1, 0
	global_load_dword v78, v176, s[0:1] nt
	s_add_u32 s0, s0, 0xc000
	s_addc_u32 s1, s1, 0
	global_load_dword v79, v176, s[0:1] nt
	s_add_u32 s0, s0, 0xc000
	s_addc_u32 s1, s1, 0
	ds_read_b128 v[96:99], v28
	ds_read_b128 v[100:103], v28 offset:16
	ds_read_b128 v[104:107], v28 offset:32
	ds_read_b128 v[108:111], v28 offset:48
	ds_read_b128 v[112:115], v28 offset:8192
	ds_read_b128 v[116:119], v28 offset:8208
	ds_read_b128 v[120:123], v28 offset:8224
	ds_read_b128 v[124:127], v28 offset:8240
	ds_read_b128 v[128:131], v28 offset:16384
	ds_read_b128 v[132:135], v28 offset:16400
	ds_read_b128 v[136:139], v28 offset:16416
	ds_read_b128 v[140:143], v28 offset:16432
	s_waitcnt vmcnt(16)
	s_waitcnt lgkmcnt(0)
	v_fmac_f32_e32 v4, v32, v96
	v_fmac_f32_e32 v5, v32, v112
	v_fmac_f32_e32 v7, v32, v128
	v_fmac_f32_e32 v4, v33, v97
	v_fmac_f32_e32 v5, v33, v113
	v_fmac_f32_e32 v7, v33, v129
	v_fmac_f32_e32 v4, v34, v98
	v_fmac_f32_e32 v5, v34, v114
	v_fmac_f32_e32 v7, v34, v130
	v_fmac_f32_e32 v4, v35, v99
	v_fmac_f32_e32 v5, v35, v115
	v_fmac_f32_e32 v7, v35, v131
	v_fmac_f32_e32 v4, v36, v100
	v_fmac_f32_e32 v5, v36, v116
	v_fmac_f32_e32 v7, v36, v132
	v_fmac_f32_e32 v4, v37, v101
	v_fmac_f32_e32 v5, v37, v117
	v_fmac_f32_e32 v7, v37, v133
	v_fmac_f32_e32 v4, v38, v102
	v_fmac_f32_e32 v5, v38, v118
	v_fmac_f32_e32 v7, v38, v134
	v_fmac_f32_e32 v4, v39, v103
	v_fmac_f32_e32 v5, v39, v119
	v_fmac_f32_e32 v7, v39, v135
	v_fmac_f32_e32 v4, v40, v104
	v_fmac_f32_e32 v5, v40, v120
	v_fmac_f32_e32 v7, v40, v136
	v_fmac_f32_e32 v4, v41, v105
	v_fmac_f32_e32 v5, v41, v121
	v_fmac_f32_e32 v7, v41, v137
	v_fmac_f32_e32 v4, v42, v106
	v_fmac_f32_e32 v5, v42, v122
	v_fmac_f32_e32 v7, v42, v138
	v_fmac_f32_e32 v4, v43, v107
	v_fmac_f32_e32 v5, v43, v123
	v_fmac_f32_e32 v7, v43, v139
	v_fmac_f32_e32 v4, v44, v108
	v_fmac_f32_e32 v5, v44, v124
	v_fmac_f32_e32 v7, v44, v140
	v_fmac_f32_e32 v4, v45, v109
	v_fmac_f32_e32 v5, v45, v125
	v_fmac_f32_e32 v7, v45, v141
	v_fmac_f32_e32 v4, v46, v110
	v_fmac_f32_e32 v5, v46, v126
	v_fmac_f32_e32 v7, v46, v142
	v_fmac_f32_e32 v4, v47, v111
	v_fmac_f32_e32 v5, v47, v127
	v_fmac_f32_e32 v7, v47, v143
	v_add_u32_e32 v28, 64, v28
	global_load_dword v32, v176, s[0:1] nt
	s_add_u32 s0, s0, 0xc000
	s_addc_u32 s1, s1, 0
	global_load_dword v33, v176, s[0:1] nt
	s_add_u32 s0, s0, 0xc000
	s_addc_u32 s1, s1, 0
	global_load_dword v34, v176, s[0:1] nt
	s_add_u32 s0, s0, 0xc000
; __global__ void __launch_bounds__(512, 2) fwd_kernel(const Args a) {
;     ...
; #pragma unroll 8
;                 for (int k = 0; k < 256; ++k) { const float w = wp[(size_t)k * 12288]; const int kk = wave * 256 + k; a0 += sl[kk] * w; a1 += sl[2048 + kk] * w; a2 += sl[4096 + kk] * w; }
	s_addc_u32 s1, s1, 0
	global_load_dword v35, v176, s[0:1] nt
	s_add_u32 s0, s0, 0xc000
	s_addc_u32 s1, s1, 0
	global_load_dword v36, v176, s[0:1] nt
	s_add_u32 s0, s0, 0xc000
	s_addc_u32 s1, s1, 0
	global_load_dword v37, v176, s[0:1] nt
	s_add_u32 s0, s0, 0xc000
	s_addc_u32 s1, s1, 0
	global_load_dword v38, v176, s[0:1] nt
	s_add_u32 s0, s0, 0xc000
	s_addc_u32 s1, s1, 0
	global_load_dword v39, v176, s[0:1] nt
	s_add_u32 s0, s0, 0xc000
	s_addc_u32 s1, s1, 0
	global_load_dword v40, v176, s[0:1] nt
	s_add_u32 s0, s0, 0xc000
	s_addc_u32 s1, s1, 0
	global_load_dword v41, v176, s[0:1] nt
	s_add_u32 s0, s0, 0xc000
	s_addc_u32 s1, s1, 0
	global_load_dword v42, v176, s[0:1] nt
	s_add_u32 s0, s0, 0xc000
	s_addc_u32 s1, s1, 0
	global_load_dword v43, v176, s[0:1] nt
	s_add_u32 s0, s0, 0xc000
	s_addc_u32 s1, s1, 0
	global_load_dword v44, v176, s[0:1] nt
	s_add_u32 s0, s0, 0xc000
	s_addc_u32 s1, s1, 0
	global_load_dword v45, v176, s[0:1] nt
	s_add_u32 s0, s0, 0xc000
	s_addc_u32 s1, s1, 0
	global_load_dword v46, v176, s[0:1] nt
	s_add_u32 s0, s0, 0xc000
	s_addc_u32 s1, s1, 0
	global_load_dword v47, v176, s[0:1] nt
	s_add_u32 s0, s0, 0xc000
	s_addc_u32 s1, s1, 0
	ds_read_b128 v[96:99], v28
	ds_read_b128 v[100:103], v28 offset:16
	ds_read_b128 v[104:107], v28 offset:32
	ds_read_b128 v[108:111], v28 offset:48
	ds_read_b128 v[112:115], v28 offset:8192
	ds_read_b128 v[116:119], v28 offset:8208
	ds_read_b128 v[120:123], v28 offset:8224
	ds_read_b128 v[124:127], v28 offset:8240
	ds_read_b128 v[128:131], v28 offset:16384
	ds_read_b128 v[132:135], v28 offset:16400
	ds_read_b128 v[136:139], v28 offset:16416
	ds_read_b128 v[140:143], v28 offset:16432
	s_waitcnt vmcnt(16)
	s_waitcnt lgkmcnt(0)
	v_fmac_f32_e32 v4, v64, v96
	v_fmac_f32_e32 v5, v64, v112
	v_fmac_f32_e32 v7, v64, v128
	v_fmac_f32_e32 v4, v65, v97
	v_fmac_f32_e32 v5, v65, v113
	v_fmac_f32_e32 v7, v65, v129
	v_fmac_f32_e32 v4, v66, v98
	v_fmac_f32_e32 v5, v66, v114
	v_fmac_f32_e32 v7, v66, v130
	v_fmac_f32_e32 v4, v67, v99
	v_fmac_f32_e32 v5, v67, v115
	v_fmac_f32_e32 v7, v67, v131
	v_fmac_f32_e32 v4, v68, v100
	v_fmac_f32_e32 v5, v68, v116
	v_fmac_f32_e32 v7, v68, v132
	v_fmac_f32_e32 v4, v69, v101
	v_fmac_f32_e32 v5, v69, v117
	v_fmac_f32_e32 v7, v69, v133
	v_fmac_f32_e32 v4, v70, v102
	v_fmac_f32_e32 v5, v70, v118
	v_fmac_f32_e32 v7, v70, v134
	v_fmac_f32_e32 v4, v71, v103
	v_fmac_f32_e32 v5, v71, v119
	v_fmac_f32_e32 v7, v71, v135
	v_fmac_f32_e32 v4, v72, v104
	v_fmac_f32_e32 v5, v72, v120
	v_fmac_f32_e32 v7, v72, v136
	v_fmac_f32_e32 v4, v73, v105
	v_fmac_f32_e32 v5, v73, v121
	v_fmac_f32_e32 v7, v73, v137
	v_fmac_f32_e32 v4, v74, v106
	v_fmac_f32_e32 v5, v74, v122
	v_fmac_f32_e32 v7, v74, v138
	v_fmac_f32_e32 v4, v75, v107
	v_fmac_f32_e32 v5, v75, v123
	v_fmac_f32_e32 v7, v75, v139
	v_fmac_f32_e32 v4, v76, v108
	v_fmac_f32_e32 v5, v76, v124
	v_fmac_f32_e32 v7, v76, v140
	v_fmac_f32_e32 v4, v77, v109
	v_fmac_f32_e32 v5, v77, v125
	v_fmac_f32_e32 v7, v77, v141
	v_fmac_f32_e32 v4, v78, v110
	v_fmac_f32_e32 v5, v78, v126
	v_fmac_f32_e32 v7, v78, v142
	v_fmac_f32_e32 v4, v79, v111
	v_fmac_f32_e32 v5, v79, v127
	v_fmac_f32_e32 v7, v79, v143
	v_add_u32_e32 v28, 64, v28
	s_add_i32 s10, s10, -1
	s_cmp_lg_u32 s10, 0
	s_cbranch_scc1 .Lada_loop
	global_load_dword v64, v176, s[0:1] nt
	s_add_u32 s0, s0, 0xc000
	s_addc_u32 s1, s1, 0
	global_load_dword v65, v176, s[0:1] nt
	s_add_u32 s0, s0, 0xc000
	s_addc_u32 s1, s1, 0
	global_load_dword v66, v176, s[0:1] nt
	s_add_u32 s0, s0, 0xc000
	s_addc_u32 s1, s1, 0
	global_load_dword v67, v176, s[0:1] nt
	s_add_u32 s0, s0, 0xc000
	s_addc_u32 s1, s1, 0
	global_load_dword v68, v176, s[0:1] nt
	s_add_u32 s0, s0, 0xc000
	s_addc_u32 s1, s1, 0
	global_load_dword v69, v176, s[0:1] nt
	s_add_u32 s0, s0, 0xc000
	s_addc_u32 s1, s1, 0
	global_load_dword v70, v176, s[0:1] nt
	s_add_u32 s0, s0, 0xc000
	s_addc_u32 s1, s1, 0
	global_load_dword v71, v176, s[0:1] nt
	s_add_u32 s0, s0, 0xc000
	s_addc_u32 s1, s1, 0
	global_load_dword v72, v176, s[0:1] nt
	s_add_u32 s0, s0, 0xc000
	s_addc_u32 s1, s1, 0
	global_load_dword v73, v176, s[0:1] nt
	s_add_u32 s0, s0, 0xc000
	s_addc_u32 s1, s1, 0
	global_load_dword v74, v176, s[0:1] nt
	s_add_u32 s0, s0, 0xc000
	s_addc_u32 s1, s1, 0
	global_load_dword v75, v176, s[0:1] nt
	s_add_u32 s0, s0, 0xc000
	s_addc_u32 s1, s1, 0
	global_load_dword v76, v176, s[0:1] nt
	s_add_u32 s0, s0, 0xc000
	s_addc_u32 s1, s1, 0
	global_load_dword v77, v176, s[0:1] nt
	s_add_u32 s0, s0, 0xc000
	s_addc_u32 s1, s1, 0
	global_load_dword v78, v176, s[0:1] nt
	s_add_u32 s0, s0, 0xc000
	s_addc_u32 s1, s1, 0
	global_load_dword v79, v176, s[0:1] nt
	s_add_u32 s0, s0, 0xc000
	s_addc_u32 s1, s1, 0
	ds_read_b128 v[96:99], v28
	ds_read_b128 v[100:103], v28 offset:16
	ds_read_b128 v[104:107], v28 offset:32
	ds_read_b128 v[108:111], v28 offset:48
	ds_read_b128 v[112:115], v28 offset:8192
	ds_read_b128 v[116:119], v28 offset:8208
	ds_read_b128 v[120:123], v28 offset:8224
	ds_read_b128 v[124:127], v28 offset:8240
	ds_read_b128 v[128:131], v28 offset:16384
	ds_read_b128 v[132:135], v28 offset:16400
	ds_read_b128 v[136:139], v28 offset:16416
	ds_read_b128 v[140:143], v28 offset:16432
	s_waitcnt vmcnt(16)
	s_waitcnt lgkmcnt(0)
; __global__ void __launch_bounds__(512, 2) fwd_kernel(const Args a) {
;     ...
;                 for (int k = 0; k < 256; ++k) { const float w = wp[(size_t)k * 12288]; const int kk = wave * 256 + k; a0 += sl[kk] * w; a1 += sl[2048 + kk] * w; a2 += sl[4096 + kk] * w; }
;                 red[(wave * 3 + 0) * 64 + lane] = a0; red[(wave * 3 + 1) * 64 + lane] = a1; red[(wave * 3 + 2) * 64 + lane] = a2;
;                 __syncthreads();
;                 if (tid < 192) { const int v = tid >> 6, jl = tid & 63; float s = ada_b[l * 12288 + j0 + jl];
; #pragma unroll
;                     for (int w8 = 0; w8 < 8; ++w8) s += red[(w8 * 3 + v) * 64 + jl];
;                     ADA[(l * 3 + v) * 12288 + j0 + jl] = s; }
	v_fmac_f32_e32 v4, v32, v96
	v_fmac_f32_e32 v5, v32, v112
	v_fmac_f32_e32 v7, v32, v128
	v_fmac_f32_e32 v4, v33, v97
	v_fmac_f32_e32 v5, v33, v113
	v_fmac_f32_e32 v7, v33, v129
	v_fmac_f32_e32 v4, v34, v98
	v_fmac_f32_e32 v5, v34, v114
	v_fmac_f32_e32 v7, v34, v130
	v_fmac_f32_e32 v4, v35, v99
	v_fmac_f32_e32 v5, v35, v115
	v_fmac_f32_e32 v7, v35, v131
	v_fmac_f32_e32 v4, v36, v100
	v_fmac_f32_e32 v5, v36, v116
	v_fmac_f32_e32 v7, v36, v132
	v_fmac_f32_e32 v4, v37, v101
	v_fmac_f32_e32 v5, v37, v117
	v_fmac_f32_e32 v7, v37, v133
	v_fmac_f32_e32 v4, v38, v102
	v_fmac_f32_e32 v5, v38, v118
	v_fmac_f32_e32 v7, v38, v134
	v_fmac_f32_e32 v4, v39, v103
	v_fmac_f32_e32 v5, v39, v119
	v_fmac_f32_e32 v7, v39, v135
	v_fmac_f32_e32 v4, v40, v104
	v_fmac_f32_e32 v5, v40, v120
	v_fmac_f32_e32 v7, v40, v136
	v_fmac_f32_e32 v4, v41, v105
	v_fmac_f32_e32 v5, v41, v121
	v_fmac_f32_e32 v7, v41, v137
	v_fmac_f32_e32 v4, v42, v106
	v_fmac_f32_e32 v5, v42, v122
	v_fmac_f32_e32 v7, v42, v138
	v_fmac_f32_e32 v4, v43, v107
	v_fmac_f32_e32 v5, v43, v123
	v_fmac_f32_e32 v7, v43, v139
	v_fmac_f32_e32 v4, v44, v108
	v_fmac_f32_e32 v5, v44, v124
	v_fmac_f32_e32 v7, v44, v140
	v_fmac_f32_e32 v4, v45, v109
	v_fmac_f32_e32 v5, v45, v125
	v_fmac_f32_e32 v7, v45, v141
	v_fmac_f32_e32 v4, v46, v110
	v_fmac_f32_e32 v5, v46, v126
	v_fmac_f32_e32 v7, v46, v142
	v_fmac_f32_e32 v4, v47, v111
	v_fmac_f32_e32 v5, v47, v127
	v_fmac_f32_e32 v7, v47, v143
	v_add_u32_e32 v28, 64, v28
	ds_read_b128 v[96:99], v28
	ds_read_b128 v[100:103], v28 offset:16
	ds_read_b128 v[104:107], v28 offset:32
	ds_read_b128 v[108:111], v28 offset:48
	ds_read_b128 v[112:115], v28 offset:8192
	ds_read_b128 v[116:119], v28 offset:8208
	ds_read_b128 v[120:123], v28 offset:8224
	ds_read_b128 v[124:127], v28 offset:8240
	ds_read_b128 v[128:131], v28 offset:16384
	ds_read_b128 v[132:135], v28 offset:16400
	ds_read_b128 v[136:139], v28 offset:16416
	ds_read_b128 v[140:143], v28 offset:16432
	s_waitcnt vmcnt(0)
	s_waitcnt lgkmcnt(0)
	v_fmac_f32_e32 v4, v64, v96
	v_fmac_f32_e32 v5, v64, v112
	v_fmac_f32_e32 v7, v64, v128
	v_fmac_f32_e32 v4, v65, v97
	v_fmac_f32_e32 v5, v65, v113
	v_fmac_f32_e32 v7, v65, v129
	v_fmac_f32_e32 v4, v66, v98
	v_fmac_f32_e32 v5, v66, v114
	v_fmac_f32_e32 v7, v66, v130
	v_fmac_f32_e32 v4, v67, v99
	v_fmac_f32_e32 v5, v67, v115
	v_fmac_f32_e32 v7, v67, v131
	v_fmac_f32_e32 v4, v68, v100
	v_fmac_f32_e32 v5, v68, v116
	v_fmac_f32_e32 v7, v68, v132
	v_fmac_f32_e32 v4, v69, v101
	v_fmac_f32_e32 v5, v69, v117
	v_fmac_f32_e32 v7, v69, v133
	v_fmac_f32_e32 v4, v70, v102
	v_fmac_f32_e32 v5, v70, v118
	v_fmac_f32_e32 v7, v70, v134
	v_fmac_f32_e32 v4, v71, v103
	v_fmac_f32_e32 v5, v71, v119
	v_fmac_f32_e32 v7, v71, v135
	v_fmac_f32_e32 v4, v72, v104
	v_fmac_f32_e32 v5, v72, v120
	v_fmac_f32_e32 v7, v72, v136
	v_fmac_f32_e32 v4, v73, v105
	v_fmac_f32_e32 v5, v73, v121
	v_fmac_f32_e32 v7, v73, v137
	v_fmac_f32_e32 v4, v74, v106
	v_fmac_f32_e32 v5, v74, v122
	v_fmac_f32_e32 v7, v74, v138
	v_fmac_f32_e32 v4, v75, v107
	v_fmac_f32_e32 v5, v75, v123
	v_fmac_f32_e32 v7, v75, v139
	v_fmac_f32_e32 v4, v76, v108
	v_fmac_f32_e32 v5, v76, v124
	v_fmac_f32_e32 v7, v76, v140
	v_fmac_f32_e32 v4, v77, v109
	v_fmac_f32_e32 v5, v77, v125
	v_fmac_f32_e32 v7, v77, v141
	v_fmac_f32_e32 v4, v78, v110
	v_fmac_f32_e32 v5, v78, v126
	v_fmac_f32_e32 v7, v78, v142
	v_fmac_f32_e32 v4, v79, v111
	v_fmac_f32_e32 v5, v79, v127
	v_fmac_f32_e32 v7, v79, v143
	v_add_u32_e32 v28, 64, v28
	ds_write2st64_b32 v1, v4, v5 offset0:96 offset1:97
	ds_write_b32 v1, v7 offset:25088
	s_waitcnt lgkmcnt(0)
	s_barrier
	s_and_saveexec_b64 s[0:1], vcc
	s_cbranch_execz .LBB0_532
	s_mul_i32 s9, s4, 0x3000
	s_add_i32 s9, s9, s8
	v_or_b32_e32 v2, s9, v188
	v_readlane_b32 s12, v252, 18
	v_ashrrev_i32_e32 v3, 31, v2
	v_readlane_b32 s22, v252, 28
	v_readlane_b32 s23, v252, 29
	v_mad_u64_u32 v[12:13], s[10:11], s4, 3, v[0:1]
	s_nop 0
	v_lshl_add_u64 v[2:3], v[2:3], 2, s[22:23]
	global_load_dword v7, v[2:3], off nt
	ds_read2st64_b32 v[2:3], v6 offset0:96 offset1:99
	ds_read2st64_b32 v[4:5], v6 offset0:102 offset1:105
	ds_read2st64_b32 v[8:9], v6 offset0:108 offset1:111
	ds_read2st64_b32 v[10:11], v6 offset0:114 offset1:117
	s_movk_i32 s4, 0x3000
	v_mul_lo_u32 v12, v12, s4
	v_add_u32_e32 v12, s8, v12
	v_readlane_b32 s16, v252, 22
	v_readlane_b32 s17, v252, 23
	v_or_b32_e32 v12, v12, v188
	v_readlane_b32 s16, v255, 42
	v_readlane_b32 s22, v255, 40
	v_ashrrev_i32_e32 v13, 31, v12
	v_readlane_b32 s17, v255, 43
	v_readlane_b32 s23, v255, 41
	v_readlane_b32 s13, v252, 19
	v_readlane_b32 s14, v252, 20
	v_readlane_b32 s15, v252, 21
	v_readlane_b32 s18, v252, 24
	v_readlane_b32 s19, v252, 25
	v_readlane_b32 s20, v252, 26
	v_readlane_b32 s21, v252, 27
	v_readlane_b32 s24, v252, 30
	v_readlane_b32 s25, v252, 31
	v_readlane_b32 s26, v252, 32
	v_readlane_b32 s27, v252, 33
	s_waitcnt vmcnt(0) lgkmcnt(3)
	v_add_f32_e32 v2, v7, v2
	v_add_f32_e32 v2, v2, v3
	s_waitcnt lgkmcnt(2)
	v_add_f32_e32 v2, v2, v4
	v_add_f32_e32 v2, v2, v5
	s_waitcnt lgkmcnt(1)
	v_add_f32_e32 v2, v2, v8
	v_add_f32_e32 v2, v2, v9
	s_waitcnt lgkmcnt(0)
	v_add_f32_e32 v2, v2, v10
	v_add_f32_e32 v4, v2, v11
	v_lshl_add_u64 v[2:3], v[12:13], 2, s[86:87]
	global_store_dword v[2:3], v4, off
	s_branch .LBB0_532
